# scan consumer: operand loads issued at the head of each step, one lgkm wait per two steps (4 register sets, prefetch distance 2)
# speedup vs baseline: 1.0144x; 1.0144x over previous
.Lscan_cons_chunk:
	v_cndmask_b32_e64 v2, v4, v5, s[42:43]
	v_add_lshl_u32 v2, v2, s80, 10
	v_mov_b32_e32 v3, v180
	s_add_i32 s28, s28, 0x10000
	v_lshl_add_u64 v[2:3], v[0:1], 0, v[2:3]
	v_add_u32_e32 v5, 64, v5
	v_subrev_u32_e32 v4, 64, v4
	s_waitcnt lgkmcnt(0)
	ds_read_b128 v[88:91], v10 offset:2304
	ds_read_b128 v[96:99], v10 offset:2816
	ds_read_b128 v[92:95], v10 offset:2560
	v_fma_mix_f32 v12, v6, v20, v180 op_sel_hi:[0,1,0]
	v_fma_mix_f32 v12, v7, v20, v12 op_sel:[0,1,0] op_sel_hi:[0,1,0]
	v_fma_mix_f32 v12, v8, v21, v12 op_sel_hi:[0,1,0]
	v_fma_mix_f32 v12, v9, v21, v12 op_sel:[0,1,0] op_sel_hi:[0,1,0]
	s_nop 1
	v_add_f32_dpp v12, v12, v12 row_ror:1 row_mask:0xf bank_mask:0xf bound_ctrl:1
	s_nop 1
	v_add_f32_dpp v12, v12, v12 row_ror:2 row_mask:0xf bank_mask:0xf bound_ctrl:1
	v_pk_fma_f32 v[48:49], v[28:29], v[66:67], v[6:7] op_sel_hi:[1,0,1]
	v_pk_fma_f32 v[50:51], v[30:31], v[66:67], v[8:9] op_sel_hi:[1,0,1]
	v_add_f32_dpp v12, v12, v12 row_ror:4 row_mask:0xf bank_mask:0xf bound_ctrl:1
	s_nop 1
	v_add_f32_dpp v12, v12, v12 row_ror:8 row_mask:0xf bank_mask:0xf bound_ctrl:1
	v_pk_fma_f32 v[6:7], v[24:25], v[12:13], v[48:49] op_sel_hi:[1,0,1] neg_lo:[1,0,0] neg_hi:[1,0,0]
	v_pk_fma_f32 v[8:9], v[26:27], v[12:13], v[50:51] op_sel_hi:[1,0,1] neg_lo:[1,0,0] neg_hi:[1,0,0]
	ds_read_b128 v[110:113], v10 offset:3328
	ds_read_b128 v[106:109], v10 offset:3072
	ds_read_b128 v[118:121], v10 offset:3840
	ds_read_b128 v[114:117], v10 offset:3584
	ds_read_b128 v[70:73], v11 offset:256
	v_fma_mix_f32 v12, v6, v36, v180 op_sel_hi:[0,1,0]
	v_fma_mix_f32 v12, v7, v36, v12 op_sel:[0,1,0] op_sel_hi:[0,1,0]
	v_fma_mix_f32 v12, v8, v37, v12 op_sel_hi:[0,1,0]
	v_fma_mix_f32 v12, v9, v37, v12 op_sel:[0,1,0] op_sel_hi:[0,1,0]
	v_fma_mix_f32 v52, v6, v22, v180 op_sel_hi:[0,1,0]
	v_fma_mix_f32 v52, v7, v22, v52 op_sel:[0,1,0] op_sel_hi:[0,1,0]
	v_add_f32_dpp v12, v12, v12 row_ror:1 row_mask:0xf bank_mask:0xf bound_ctrl:1
	v_fma_mix_f32 v52, v8, v23, v52 op_sel_hi:[0,1,0]
	v_fma_mix_f32 v52, v9, v23, v52 op_sel:[0,1,0] op_sel_hi:[0,1,0]
	v_add_f32_dpp v12, v12, v12 row_ror:2 row_mask:0xf bank_mask:0xf bound_ctrl:1
	v_pk_fma_f32 v[48:49], v[44:45], v[66:67], v[6:7] op_sel:[0,1,0]
	v_pk_fma_f32 v[50:51], v[46:47], v[66:67], v[8:9] op_sel:[0,1,0]
	v_add_f32_dpp v12, v12, v12 row_ror:4 row_mask:0xf bank_mask:0xf bound_ctrl:1
	s_nop 1
	v_add_f32_dpp v12, v12, v12 row_ror:8 row_mask:0xf bank_mask:0xf bound_ctrl:1
	v_pk_fma_f32 v[6:7], v[40:41], v[12:13], v[48:49] op_sel_hi:[1,0,1] neg_lo:[1,0,0] neg_hi:[1,0,0]
	v_pk_fma_f32 v[8:9], v[42:43], v[12:13], v[50:51] op_sel_hi:[1,0,1] neg_lo:[1,0,0] neg_hi:[1,0,0]
	s_waitcnt lgkmcnt(1)
	ds_read_b128 v[20:23], v10 offset:4352
	ds_read_b128 v[28:31], v10 offset:4864
	ds_read_b128 v[24:27], v10 offset:4608
	v_fma_mix_f32 v12, v6, v88, v180 op_sel_hi:[0,1,0]
	v_fma_mix_f32 v12, v7, v88, v12 op_sel:[0,1,0] op_sel_hi:[0,1,0]
	v_fma_mix_f32 v12, v8, v89, v12 op_sel_hi:[0,1,0]
	v_fma_mix_f32 v12, v9, v89, v12 op_sel:[0,1,0] op_sel_hi:[0,1,0]
	v_fma_mix_f32 v53, v6, v38, v180 op_sel_hi:[0,1,0]
	v_fma_mix_f32 v53, v7, v38, v53 op_sel:[0,1,0] op_sel_hi:[0,1,0]
	v_add_f32_dpp v12, v12, v12 row_ror:1 row_mask:0xf bank_mask:0xf bound_ctrl:1
	v_fma_mix_f32 v53, v8, v39, v53 op_sel_hi:[0,1,0]
	v_fma_mix_f32 v53, v9, v39, v53 op_sel:[0,1,0] op_sel_hi:[0,1,0]
	v_add_f32_dpp v12, v12, v12 row_ror:2 row_mask:0xf bank_mask:0xf bound_ctrl:1
	v_pk_fma_f32 v[48:49], v[96:97], v[68:69], v[6:7] op_sel_hi:[1,0,1]
	v_pk_fma_f32 v[50:51], v[98:99], v[68:69], v[8:9] op_sel_hi:[1,0,1]
	v_add_f32_dpp v12, v12, v12 row_ror:4 row_mask:0xf bank_mask:0xf bound_ctrl:1
	s_nop 1
	v_add_f32_dpp v12, v12, v12 row_ror:8 row_mask:0xf bank_mask:0xf bound_ctrl:1
	v_pk_fma_f32 v[6:7], v[92:93], v[12:13], v[48:49] op_sel_hi:[1,0,1] neg_lo:[1,0,0] neg_hi:[1,0,0]
	v_pk_fma_f32 v[8:9], v[94:95], v[12:13], v[50:51] op_sel_hi:[1,0,1] neg_lo:[1,0,0] neg_hi:[1,0,0]
	ds_read_b128 v[36:39], v10 offset:5376
	ds_read_b128 v[44:47], v10 offset:5888
	ds_read_b128 v[40:43], v10 offset:5632
	v_fma_mix_f32 v12, v6, v110, v180 op_sel_hi:[0,1,0]
	v_fma_mix_f32 v12, v7, v110, v12 op_sel:[0,1,0] op_sel_hi:[0,1,0]
	v_fma_mix_f32 v12, v8, v111, v12 op_sel_hi:[0,1,0]
	v_fma_mix_f32 v12, v9, v111, v12 op_sel:[0,1,0] op_sel_hi:[0,1,0]
	v_fma_mix_f32 v54, v6, v90, v180 op_sel_hi:[0,1,0]
	v_fma_mix_f32 v54, v7, v90, v54 op_sel:[0,1,0] op_sel_hi:[0,1,0]
	v_add_f32_dpp v12, v12, v12 row_ror:1 row_mask:0xf bank_mask:0xf bound_ctrl:1
	v_fma_mix_f32 v54, v8, v91, v54 op_sel_hi:[0,1,0]
	v_fma_mix_f32 v54, v9, v91, v54 op_sel:[0,1,0] op_sel_hi:[0,1,0]
	v_add_f32_dpp v12, v12, v12 row_ror:2 row_mask:0xf bank_mask:0xf bound_ctrl:1
	v_pk_fma_f32 v[48:49], v[118:119], v[68:69], v[6:7] op_sel:[0,1,0]
	v_pk_fma_f32 v[50:51], v[120:121], v[68:69], v[8:9] op_sel:[0,1,0]
	v_add_f32_dpp v12, v12, v12 row_ror:4 row_mask:0xf bank_mask:0xf bound_ctrl:1
	s_nop 1
	v_add_f32_dpp v12, v12, v12 row_ror:8 row_mask:0xf bank_mask:0xf bound_ctrl:1
	v_pk_fma_f32 v[6:7], v[114:115], v[12:13], v[48:49] op_sel_hi:[1,0,1] neg_lo:[1,0,0] neg_hi:[1,0,0]
	v_pk_fma_f32 v[8:9], v[116:117], v[12:13], v[50:51] op_sel_hi:[1,0,1] neg_lo:[1,0,0] neg_hi:[1,0,0]
	v_pk_mul_f32 v[6:7], v[6:7], v[106:107]
	v_pk_mul_f32 v[8:9], v[8:9], v[108:109]
	s_waitcnt lgkmcnt(0)
	ds_read_b128 v[88:91], v10 offset:6400
	ds_read_b128 v[96:99], v10 offset:6912
	ds_read_b128 v[92:95], v10 offset:6656
	v_fma_mix_f32 v12, v6, v20, v180 op_sel_hi:[0,1,0]
	v_fma_mix_f32 v12, v7, v20, v12 op_sel:[0,1,0] op_sel_hi:[0,1,0]
	v_fma_mix_f32 v12, v8, v21, v12 op_sel_hi:[0,1,0]
	v_fma_mix_f32 v12, v9, v21, v12 op_sel:[0,1,0] op_sel_hi:[0,1,0]
	v_fma_mix_f32 v55, v6, v112, v180 op_sel_hi:[0,1,0]
	v_fma_mix_f32 v55, v7, v112, v55 op_sel:[0,1,0] op_sel_hi:[0,1,0]
	v_add_f32_dpp v12, v12, v12 row_ror:1 row_mask:0xf bank_mask:0xf bound_ctrl:1
	v_fma_mix_f32 v55, v8, v113, v55 op_sel_hi:[0,1,0]
	v_fma_mix_f32 v55, v9, v113, v55 op_sel:[0,1,0] op_sel_hi:[0,1,0]
	v_add_f32_dpp v12, v12, v12 row_ror:2 row_mask:0xf bank_mask:0xf bound_ctrl:1
	v_pk_fma_f32 v[48:49], v[28:29], v[70:71], v[6:7] op_sel_hi:[1,0,1]
	v_pk_fma_f32 v[50:51], v[30:31], v[70:71], v[8:9] op_sel_hi:[1,0,1]
	v_add_f32_dpp v12, v12, v12 row_ror:4 row_mask:0xf bank_mask:0xf bound_ctrl:1
	s_nop 1
	v_add_f32_dpp v12, v12, v12 row_ror:8 row_mask:0xf bank_mask:0xf bound_ctrl:1
	v_pk_fma_f32 v[6:7], v[24:25], v[12:13], v[48:49] op_sel_hi:[1,0,1] neg_lo:[1,0,0] neg_hi:[1,0,0]
	v_pk_fma_f32 v[8:9], v[26:27], v[12:13], v[50:51] op_sel_hi:[1,0,1] neg_lo:[1,0,0] neg_hi:[1,0,0]
	ds_read_b128 v[110:113], v10 offset:7424
	ds_read_b128 v[106:109], v10 offset:7168
	ds_read_b128 v[118:121], v10 offset:7936
	ds_read_b128 v[114:117], v10 offset:7680
	ds_read_b128 v[66:69], v11 offset:512
	v_fma_mix_f32 v12, v6, v36, v180 op_sel_hi:[0,1,0]
	v_fma_mix_f32 v12, v7, v36, v12 op_sel:[0,1,0] op_sel_hi:[0,1,0]
	v_fma_mix_f32 v12, v8, v37, v12 op_sel_hi:[0,1,0]
	v_fma_mix_f32 v12, v9, v37, v12 op_sel:[0,1,0] op_sel_hi:[0,1,0]
	v_fma_mix_f32 v56, v6, v22, v180 op_sel_hi:[0,1,0]
	v_fma_mix_f32 v56, v7, v22, v56 op_sel:[0,1,0] op_sel_hi:[0,1,0]
	v_add_f32_dpp v12, v12, v12 row_ror:1 row_mask:0xf bank_mask:0xf bound_ctrl:1
	v_fma_mix_f32 v56, v8, v23, v56 op_sel_hi:[0,1,0]
	v_fma_mix_f32 v56, v9, v23, v56 op_sel:[0,1,0] op_sel_hi:[0,1,0]
	v_add_f32_dpp v12, v12, v12 row_ror:2 row_mask:0xf bank_mask:0xf bound_ctrl:1
	v_pk_fma_f32 v[48:49], v[44:45], v[70:71], v[6:7] op_sel:[0,1,0]
	v_pk_fma_f32 v[50:51], v[46:47], v[70:71], v[8:9] op_sel:[0,1,0]
	v_add_f32_dpp v12, v12, v12 row_ror:4 row_mask:0xf bank_mask:0xf bound_ctrl:1
	s_nop 1
	v_add_f32_dpp v12, v12, v12 row_ror:8 row_mask:0xf bank_mask:0xf bound_ctrl:1
	v_pk_fma_f32 v[6:7], v[40:41], v[12:13], v[48:49] op_sel_hi:[1,0,1] neg_lo:[1,0,0] neg_hi:[1,0,0]
	v_pk_fma_f32 v[8:9], v[42:43], v[12:13], v[50:51] op_sel_hi:[1,0,1] neg_lo:[1,0,0] neg_hi:[1,0,0]
	s_waitcnt lgkmcnt(1)
	ds_read_b128 v[20:23], v10 offset:8448
	ds_read_b128 v[28:31], v10 offset:8960
	ds_read_b128 v[24:27], v10 offset:8704
	v_fma_mix_f32 v12, v6, v88, v180 op_sel_hi:[0,1,0]
	v_fma_mix_f32 v12, v7, v88, v12 op_sel:[0,1,0] op_sel_hi:[0,1,0]
	v_fma_mix_f32 v12, v8, v89, v12 op_sel_hi:[0,1,0]
	v_fma_mix_f32 v12, v9, v89, v12 op_sel:[0,1,0] op_sel_hi:[0,1,0]
	v_fma_mix_f32 v57, v6, v38, v180 op_sel_hi:[0,1,0]
	v_fma_mix_f32 v57, v7, v38, v57 op_sel:[0,1,0] op_sel_hi:[0,1,0]
	v_add_f32_dpp v12, v12, v12 row_ror:1 row_mask:0xf bank_mask:0xf bound_ctrl:1
	v_fma_mix_f32 v57, v8, v39, v57 op_sel_hi:[0,1,0]
	v_fma_mix_f32 v57, v9, v39, v57 op_sel:[0,1,0] op_sel_hi:[0,1,0]
	v_add_f32_dpp v12, v12, v12 row_ror:2 row_mask:0xf bank_mask:0xf bound_ctrl:1
	v_pk_fma_f32 v[48:49], v[96:97], v[72:73], v[6:7] op_sel_hi:[1,0,1]
	v_pk_fma_f32 v[50:51], v[98:99], v[72:73], v[8:9] op_sel_hi:[1,0,1]
	v_add_f32_dpp v12, v12, v12 row_ror:4 row_mask:0xf bank_mask:0xf bound_ctrl:1
	s_nop 1
	v_add_f32_dpp v12, v12, v12 row_ror:8 row_mask:0xf bank_mask:0xf bound_ctrl:1
	v_pk_fma_f32 v[6:7], v[92:93], v[12:13], v[48:49] op_sel_hi:[1,0,1] neg_lo:[1,0,0] neg_hi:[1,0,0]
	v_pk_fma_f32 v[8:9], v[94:95], v[12:13], v[50:51] op_sel_hi:[1,0,1] neg_lo:[1,0,0] neg_hi:[1,0,0]
	ds_read_b128 v[36:39], v10 offset:9472
	ds_read_b128 v[44:47], v10 offset:9984
	ds_read_b128 v[40:43], v10 offset:9728
	v_fma_mix_f32 v12, v6, v110, v180 op_sel_hi:[0,1,0]
	v_fma_mix_f32 v12, v7, v110, v12 op_sel:[0,1,0] op_sel_hi:[0,1,0]
	v_fma_mix_f32 v12, v8, v111, v12 op_sel_hi:[0,1,0]
	v_fma_mix_f32 v12, v9, v111, v12 op_sel:[0,1,0] op_sel_hi:[0,1,0]
	v_fma_mix_f32 v81, v6, v90, v180 op_sel_hi:[0,1,0]
	v_fma_mix_f32 v81, v7, v90, v81 op_sel:[0,1,0] op_sel_hi:[0,1,0]
	v_add_f32_dpp v12, v12, v12 row_ror:1 row_mask:0xf bank_mask:0xf bound_ctrl:1
	v_fma_mix_f32 v81, v8, v91, v81 op_sel_hi:[0,1,0]
	v_fma_mix_f32 v81, v9, v91, v81 op_sel:[0,1,0] op_sel_hi:[0,1,0]
	v_add_f32_dpp v12, v12, v12 row_ror:2 row_mask:0xf bank_mask:0xf bound_ctrl:1
	v_pk_fma_f32 v[48:49], v[118:119], v[72:73], v[6:7] op_sel:[0,1,0]
	v_pk_fma_f32 v[50:51], v[120:121], v[72:73], v[8:9] op_sel:[0,1,0]
	v_add_f32_dpp v12, v12, v12 row_ror:4 row_mask:0xf bank_mask:0xf bound_ctrl:1
	s_nop 1
	v_add_f32_dpp v12, v12, v12 row_ror:8 row_mask:0xf bank_mask:0xf bound_ctrl:1
	v_pk_fma_f32 v[6:7], v[114:115], v[12:13], v[48:49] op_sel_hi:[1,0,1] neg_lo:[1,0,0] neg_hi:[1,0,0]
	v_pk_fma_f32 v[8:9], v[116:117], v[12:13], v[50:51] op_sel_hi:[1,0,1] neg_lo:[1,0,0] neg_hi:[1,0,0]
	v_pk_mul_f32 v[6:7], v[6:7], v[106:107]
	v_pk_mul_f32 v[8:9], v[8:9], v[108:109]
	s_waitcnt lgkmcnt(0)
	ds_read_b128 v[88:91], v10 offset:10496
	ds_read_b128 v[96:99], v10 offset:11008
	ds_read_b128 v[92:95], v10 offset:10752
	v_fma_mix_f32 v12, v6, v20, v180 op_sel_hi:[0,1,0]
	v_fma_mix_f32 v12, v7, v20, v12 op_sel:[0,1,0] op_sel_hi:[0,1,0]
	v_fma_mix_f32 v12, v8, v21, v12 op_sel_hi:[0,1,0]
	v_fma_mix_f32 v12, v9, v21, v12 op_sel:[0,1,0] op_sel_hi:[0,1,0]
	v_fma_mix_f32 v82, v6, v112, v180 op_sel_hi:[0,1,0]
	v_fma_mix_f32 v82, v7, v112, v82 op_sel:[0,1,0] op_sel_hi:[0,1,0]
	v_add_f32_dpp v12, v12, v12 row_ror:1 row_mask:0xf bank_mask:0xf bound_ctrl:1
	v_fma_mix_f32 v82, v8, v113, v82 op_sel_hi:[0,1,0]
	v_fma_mix_f32 v82, v9, v113, v82 op_sel:[0,1,0] op_sel_hi:[0,1,0]
	v_add_f32_dpp v12, v12, v12 row_ror:2 row_mask:0xf bank_mask:0xf bound_ctrl:1
	v_pk_fma_f32 v[48:49], v[28:29], v[66:67], v[6:7] op_sel_hi:[1,0,1]
	v_pk_fma_f32 v[50:51], v[30:31], v[66:67], v[8:9] op_sel_hi:[1,0,1]
	v_add_f32_dpp v12, v12, v12 row_ror:4 row_mask:0xf bank_mask:0xf bound_ctrl:1
	s_nop 1
	v_add_f32_dpp v12, v12, v12 row_ror:8 row_mask:0xf bank_mask:0xf bound_ctrl:1
	v_pk_fma_f32 v[6:7], v[24:25], v[12:13], v[48:49] op_sel_hi:[1,0,1] neg_lo:[1,0,0] neg_hi:[1,0,0]
	v_pk_fma_f32 v[8:9], v[26:27], v[12:13], v[50:51] op_sel_hi:[1,0,1] neg_lo:[1,0,0] neg_hi:[1,0,0]
	ds_read_b128 v[110:113], v10 offset:11520
	ds_read_b128 v[106:109], v10 offset:11264
	ds_read_b128 v[118:121], v10 offset:12032
	ds_read_b128 v[114:117], v10 offset:11776
	ds_read_b128 v[70:73], v11 offset:768
	v_fma_mix_f32 v12, v6, v36, v180 op_sel_hi:[0,1,0]
	v_fma_mix_f32 v12, v7, v36, v12 op_sel:[0,1,0] op_sel_hi:[0,1,0]
	v_fma_mix_f32 v12, v8, v37, v12 op_sel_hi:[0,1,0]
	v_fma_mix_f32 v12, v9, v37, v12 op_sel:[0,1,0] op_sel_hi:[0,1,0]
	v_fma_mix_f32 v83, v6, v22, v180 op_sel_hi:[0,1,0]
	v_fma_mix_f32 v83, v7, v22, v83 op_sel:[0,1,0] op_sel_hi:[0,1,0]
	v_add_f32_dpp v12, v12, v12 row_ror:1 row_mask:0xf bank_mask:0xf bound_ctrl:1
	v_fma_mix_f32 v83, v8, v23, v83 op_sel_hi:[0,1,0]
	v_fma_mix_f32 v83, v9, v23, v83 op_sel:[0,1,0] op_sel_hi:[0,1,0]
	v_add_f32_dpp v12, v12, v12 row_ror:2 row_mask:0xf bank_mask:0xf bound_ctrl:1
	v_pk_fma_f32 v[48:49], v[44:45], v[66:67], v[6:7] op_sel:[0,1,0]
	v_pk_fma_f32 v[50:51], v[46:47], v[66:67], v[8:9] op_sel:[0,1,0]
	v_add_f32_dpp v12, v12, v12 row_ror:4 row_mask:0xf bank_mask:0xf bound_ctrl:1
	s_nop 1
	v_add_f32_dpp v12, v12, v12 row_ror:8 row_mask:0xf bank_mask:0xf bound_ctrl:1
	v_pk_fma_f32 v[6:7], v[40:41], v[12:13], v[48:49] op_sel_hi:[1,0,1] neg_lo:[1,0,0] neg_hi:[1,0,0]
	v_pk_fma_f32 v[8:9], v[42:43], v[12:13], v[50:51] op_sel_hi:[1,0,1] neg_lo:[1,0,0] neg_hi:[1,0,0]
	s_waitcnt lgkmcnt(1)
	ds_read_b128 v[20:23], v10 offset:12544
	ds_read_b128 v[28:31], v10 offset:13056
	ds_read_b128 v[24:27], v10 offset:12800
	v_fma_mix_f32 v12, v6, v88, v180 op_sel_hi:[0,1,0]
	v_fma_mix_f32 v12, v7, v88, v12 op_sel:[0,1,0] op_sel_hi:[0,1,0]
	v_fma_mix_f32 v12, v8, v89, v12 op_sel_hi:[0,1,0]
	v_fma_mix_f32 v12, v9, v89, v12 op_sel:[0,1,0] op_sel_hi:[0,1,0]
	v_fma_mix_f32 v100, v6, v38, v180 op_sel_hi:[0,1,0]
	v_fma_mix_f32 v100, v7, v38, v100 op_sel:[0,1,0] op_sel_hi:[0,1,0]
	v_add_f32_dpp v12, v12, v12 row_ror:1 row_mask:0xf bank_mask:0xf bound_ctrl:1
	v_fma_mix_f32 v100, v8, v39, v100 op_sel_hi:[0,1,0]
	v_fma_mix_f32 v100, v9, v39, v100 op_sel:[0,1,0] op_sel_hi:[0,1,0]
	v_add_f32_dpp v12, v12, v12 row_ror:2 row_mask:0xf bank_mask:0xf bound_ctrl:1
	v_pk_fma_f32 v[48:49], v[96:97], v[68:69], v[6:7] op_sel_hi:[1,0,1]
	v_pk_fma_f32 v[50:51], v[98:99], v[68:69], v[8:9] op_sel_hi:[1,0,1]
	v_add_f32_dpp v12, v12, v12 row_ror:4 row_mask:0xf bank_mask:0xf bound_ctrl:1
	s_nop 1
	v_add_f32_dpp v12, v12, v12 row_ror:8 row_mask:0xf bank_mask:0xf bound_ctrl:1
	v_pk_fma_f32 v[6:7], v[92:93], v[12:13], v[48:49] op_sel_hi:[1,0,1] neg_lo:[1,0,0] neg_hi:[1,0,0]
	v_pk_fma_f32 v[8:9], v[94:95], v[12:13], v[50:51] op_sel_hi:[1,0,1] neg_lo:[1,0,0] neg_hi:[1,0,0]
	ds_read_b128 v[36:39], v10 offset:13568
	ds_read_b128 v[44:47], v10 offset:14080
	ds_read_b128 v[40:43], v10 offset:13824
	v_fma_mix_f32 v12, v6, v110, v180 op_sel_hi:[0,1,0]
	v_fma_mix_f32 v12, v7, v110, v12 op_sel:[0,1,0] op_sel_hi:[0,1,0]
	v_fma_mix_f32 v12, v8, v111, v12 op_sel_hi:[0,1,0]
	v_fma_mix_f32 v12, v9, v111, v12 op_sel:[0,1,0] op_sel_hi:[0,1,0]
	v_fma_mix_f32 v101, v6, v90, v180 op_sel_hi:[0,1,0]
	v_fma_mix_f32 v101, v7, v90, v101 op_sel:[0,1,0] op_sel_hi:[0,1,0]
	v_add_f32_dpp v12, v12, v12 row_ror:1 row_mask:0xf bank_mask:0xf bound_ctrl:1
	v_fma_mix_f32 v101, v8, v91, v101 op_sel_hi:[0,1,0]
	v_fma_mix_f32 v101, v9, v91, v101 op_sel:[0,1,0] op_sel_hi:[0,1,0]
	v_add_f32_dpp v12, v12, v12 row_ror:2 row_mask:0xf bank_mask:0xf bound_ctrl:1
	v_pk_fma_f32 v[48:49], v[118:119], v[68:69], v[6:7] op_sel:[0,1,0]
	v_pk_fma_f32 v[50:51], v[120:121], v[68:69], v[8:9] op_sel:[0,1,0]
	v_add_f32_dpp v12, v12, v12 row_ror:4 row_mask:0xf bank_mask:0xf bound_ctrl:1
	s_nop 1
	v_add_f32_dpp v12, v12, v12 row_ror:8 row_mask:0xf bank_mask:0xf bound_ctrl:1
	v_pk_fma_f32 v[6:7], v[114:115], v[12:13], v[48:49] op_sel_hi:[1,0,1] neg_lo:[1,0,0] neg_hi:[1,0,0]
	v_pk_fma_f32 v[8:9], v[116:117], v[12:13], v[50:51] op_sel_hi:[1,0,1] neg_lo:[1,0,0] neg_hi:[1,0,0]
	v_pk_mul_f32 v[6:7], v[6:7], v[106:107]
	v_pk_mul_f32 v[8:9], v[8:9], v[108:109]
	s_waitcnt lgkmcnt(0)
	ds_read_b128 v[88:91], v10 offset:14592
	ds_read_b128 v[96:99], v10 offset:15104
	ds_read_b128 v[92:95], v10 offset:14848
	v_fma_mix_f32 v12, v6, v20, v180 op_sel_hi:[0,1,0]
	v_fma_mix_f32 v12, v7, v20, v12 op_sel:[0,1,0] op_sel_hi:[0,1,0]
	v_fma_mix_f32 v12, v8, v21, v12 op_sel_hi:[0,1,0]
	v_fma_mix_f32 v12, v9, v21, v12 op_sel:[0,1,0] op_sel_hi:[0,1,0]
	v_fma_mix_f32 v102, v6, v112, v180 op_sel_hi:[0,1,0]
	v_fma_mix_f32 v102, v7, v112, v102 op_sel:[0,1,0] op_sel_hi:[0,1,0]
	v_add_f32_dpp v12, v12, v12 row_ror:1 row_mask:0xf bank_mask:0xf bound_ctrl:1
	v_fma_mix_f32 v102, v8, v113, v102 op_sel_hi:[0,1,0]
	v_fma_mix_f32 v102, v9, v113, v102 op_sel:[0,1,0] op_sel_hi:[0,1,0]
	v_add_f32_dpp v12, v12, v12 row_ror:2 row_mask:0xf bank_mask:0xf bound_ctrl:1
	v_pk_fma_f32 v[48:49], v[28:29], v[70:71], v[6:7] op_sel_hi:[1,0,1]
	v_pk_fma_f32 v[50:51], v[30:31], v[70:71], v[8:9] op_sel_hi:[1,0,1]
	v_add_f32_dpp v12, v12, v12 row_ror:4 row_mask:0xf bank_mask:0xf bound_ctrl:1
	s_nop 1
	v_add_f32_dpp v12, v12, v12 row_ror:8 row_mask:0xf bank_mask:0xf bound_ctrl:1
	v_pk_fma_f32 v[6:7], v[24:25], v[12:13], v[48:49] op_sel_hi:[1,0,1] neg_lo:[1,0,0] neg_hi:[1,0,0]
	v_pk_fma_f32 v[8:9], v[26:27], v[12:13], v[50:51] op_sel_hi:[1,0,1] neg_lo:[1,0,0] neg_hi:[1,0,0]
	ds_read_b128 v[110:113], v10 offset:15616
	ds_read_b128 v[106:109], v10 offset:15360
	ds_read_b128 v[118:121], v10 offset:16128
	ds_read_b128 v[114:117], v10 offset:15872
	ds_read_b128 v[66:69], v11 offset:1024
	v_fma_mix_f32 v12, v6, v36, v180 op_sel_hi:[0,1,0]
	v_fma_mix_f32 v12, v7, v36, v12 op_sel:[0,1,0] op_sel_hi:[0,1,0]
	v_fma_mix_f32 v12, v8, v37, v12 op_sel_hi:[0,1,0]
	v_fma_mix_f32 v12, v9, v37, v12 op_sel:[0,1,0] op_sel_hi:[0,1,0]
	v_fma_mix_f32 v103, v6, v22, v180 op_sel_hi:[0,1,0]
	v_fma_mix_f32 v103, v7, v22, v103 op_sel:[0,1,0] op_sel_hi:[0,1,0]
	v_add_f32_dpp v12, v12, v12 row_ror:1 row_mask:0xf bank_mask:0xf bound_ctrl:1
	v_fma_mix_f32 v103, v8, v23, v103 op_sel_hi:[0,1,0]
	v_fma_mix_f32 v103, v9, v23, v103 op_sel:[0,1,0] op_sel_hi:[0,1,0]
	v_add_f32_dpp v12, v12, v12 row_ror:2 row_mask:0xf bank_mask:0xf bound_ctrl:1
	v_pk_fma_f32 v[48:49], v[44:45], v[70:71], v[6:7] op_sel:[0,1,0]
	v_pk_fma_f32 v[50:51], v[46:47], v[70:71], v[8:9] op_sel:[0,1,0]
	v_add_f32_dpp v12, v12, v12 row_ror:4 row_mask:0xf bank_mask:0xf bound_ctrl:1
	s_nop 1
	v_add_f32_dpp v12, v12, v12 row_ror:8 row_mask:0xf bank_mask:0xf bound_ctrl:1
	v_pk_fma_f32 v[6:7], v[40:41], v[12:13], v[48:49] op_sel_hi:[1,0,1] neg_lo:[1,0,0] neg_hi:[1,0,0]
	v_pk_fma_f32 v[8:9], v[42:43], v[12:13], v[50:51] op_sel_hi:[1,0,1] neg_lo:[1,0,0] neg_hi:[1,0,0]
	s_waitcnt lgkmcnt(1)
	ds_read_b128 v[20:23], v10 offset:16640
	ds_read_b128 v[28:31], v10 offset:17152
	ds_read_b128 v[24:27], v10 offset:16896
	v_fma_mix_f32 v12, v6, v88, v180 op_sel_hi:[0,1,0]
	v_fma_mix_f32 v12, v7, v88, v12 op_sel:[0,1,0] op_sel_hi:[0,1,0]
	v_fma_mix_f32 v12, v8, v89, v12 op_sel_hi:[0,1,0]
	v_fma_mix_f32 v12, v9, v89, v12 op_sel:[0,1,0] op_sel_hi:[0,1,0]
	v_fma_mix_f32 v104, v6, v38, v180 op_sel_hi:[0,1,0]
	v_fma_mix_f32 v104, v7, v38, v104 op_sel:[0,1,0] op_sel_hi:[0,1,0]
	v_add_f32_dpp v12, v12, v12 row_ror:1 row_mask:0xf bank_mask:0xf bound_ctrl:1
	v_fma_mix_f32 v104, v8, v39, v104 op_sel_hi:[0,1,0]
	v_fma_mix_f32 v104, v9, v39, v104 op_sel:[0,1,0] op_sel_hi:[0,1,0]
	v_add_f32_dpp v12, v12, v12 row_ror:2 row_mask:0xf bank_mask:0xf bound_ctrl:1
	v_pk_fma_f32 v[48:49], v[96:97], v[72:73], v[6:7] op_sel_hi:[1,0,1]
	v_pk_fma_f32 v[50:51], v[98:99], v[72:73], v[8:9] op_sel_hi:[1,0,1]
	v_add_f32_dpp v12, v12, v12 row_ror:4 row_mask:0xf bank_mask:0xf bound_ctrl:1
	s_nop 1
	v_add_f32_dpp v12, v12, v12 row_ror:8 row_mask:0xf bank_mask:0xf bound_ctrl:1
	v_pk_fma_f32 v[6:7], v[92:93], v[12:13], v[48:49] op_sel_hi:[1,0,1] neg_lo:[1,0,0] neg_hi:[1,0,0]
	v_pk_fma_f32 v[8:9], v[94:95], v[12:13], v[50:51] op_sel_hi:[1,0,1] neg_lo:[1,0,0] neg_hi:[1,0,0]
	ds_read_b128 v[36:39], v10 offset:17664
	ds_read_b128 v[44:47], v10 offset:18176
	ds_read_b128 v[40:43], v10 offset:17920
	v_fma_mix_f32 v12, v6, v110, v180 op_sel_hi:[0,1,0]
	v_fma_mix_f32 v12, v7, v110, v12 op_sel:[0,1,0] op_sel_hi:[0,1,0]
	v_fma_mix_f32 v12, v8, v111, v12 op_sel_hi:[0,1,0]
	v_fma_mix_f32 v12, v9, v111, v12 op_sel:[0,1,0] op_sel_hi:[0,1,0]
	v_fma_mix_f32 v105, v6, v90, v180 op_sel_hi:[0,1,0]
	v_fma_mix_f32 v105, v7, v90, v105 op_sel:[0,1,0] op_sel_hi:[0,1,0]
	v_add_f32_dpp v12, v12, v12 row_ror:1 row_mask:0xf bank_mask:0xf bound_ctrl:1
	v_fma_mix_f32 v105, v8, v91, v105 op_sel_hi:[0,1,0]
	v_fma_mix_f32 v105, v9, v91, v105 op_sel:[0,1,0] op_sel_hi:[0,1,0]
	v_add_f32_dpp v12, v12, v12 row_ror:2 row_mask:0xf bank_mask:0xf bound_ctrl:1
	v_pk_fma_f32 v[48:49], v[118:119], v[72:73], v[6:7] op_sel:[0,1,0]
	v_pk_fma_f32 v[50:51], v[120:121], v[72:73], v[8:9] op_sel:[0,1,0]
	v_add_f32_dpp v12, v12, v12 row_ror:4 row_mask:0xf bank_mask:0xf bound_ctrl:1
	s_nop 1
	v_add_f32_dpp v12, v12, v12 row_ror:8 row_mask:0xf bank_mask:0xf bound_ctrl:1
	v_pk_fma_f32 v[6:7], v[114:115], v[12:13], v[48:49] op_sel_hi:[1,0,1] neg_lo:[1,0,0] neg_hi:[1,0,0]
	v_pk_fma_f32 v[8:9], v[116:117], v[12:13], v[50:51] op_sel_hi:[1,0,1] neg_lo:[1,0,0] neg_hi:[1,0,0]
	v_pk_mul_f32 v[6:7], v[6:7], v[106:107]
	v_pk_mul_f32 v[8:9], v[8:9], v[108:109]
	s_waitcnt lgkmcnt(0)
	ds_read_b128 v[88:91], v10 offset:18688
	ds_read_b128 v[96:99], v10 offset:19200
	ds_read_b128 v[92:95], v10 offset:18944
	v_fma_mix_f32 v12, v6, v20, v180 op_sel_hi:[0,1,0]
	v_fma_mix_f32 v12, v7, v20, v12 op_sel:[0,1,0] op_sel_hi:[0,1,0]
	v_fma_mix_f32 v12, v8, v21, v12 op_sel_hi:[0,1,0]
	v_fma_mix_f32 v12, v9, v21, v12 op_sel:[0,1,0] op_sel_hi:[0,1,0]
	v_fma_mix_f32 v61, v6, v112, v180 op_sel_hi:[0,1,0]
	v_fma_mix_f32 v61, v7, v112, v61 op_sel:[0,1,0] op_sel_hi:[0,1,0]
	v_add_f32_dpp v12, v12, v12 row_ror:1 row_mask:0xf bank_mask:0xf bound_ctrl:1
	v_fma_mix_f32 v61, v8, v113, v61 op_sel_hi:[0,1,0]
	v_fma_mix_f32 v61, v9, v113, v61 op_sel:[0,1,0] op_sel_hi:[0,1,0]
	v_add_f32_dpp v12, v12, v12 row_ror:2 row_mask:0xf bank_mask:0xf bound_ctrl:1
	v_pk_fma_f32 v[48:49], v[28:29], v[66:67], v[6:7] op_sel_hi:[1,0,1]
	v_pk_fma_f32 v[50:51], v[30:31], v[66:67], v[8:9] op_sel_hi:[1,0,1]
	v_add_f32_dpp v12, v12, v12 row_ror:4 row_mask:0xf bank_mask:0xf bound_ctrl:1
	s_nop 1
	v_add_f32_dpp v12, v12, v12 row_ror:8 row_mask:0xf bank_mask:0xf bound_ctrl:1
	v_pk_fma_f32 v[6:7], v[24:25], v[12:13], v[48:49] op_sel_hi:[1,0,1] neg_lo:[1,0,0] neg_hi:[1,0,0]
	v_pk_fma_f32 v[8:9], v[26:27], v[12:13], v[50:51] op_sel_hi:[1,0,1] neg_lo:[1,0,0] neg_hi:[1,0,0]
	ds_read_b128 v[110:113], v10 offset:19712
	ds_read_b128 v[106:109], v10 offset:19456
	ds_read_b128 v[118:121], v10 offset:20224
	ds_read_b128 v[114:117], v10 offset:19968
	ds_read_b128 v[70:73], v11 offset:1280
	v_fma_mix_f32 v12, v6, v36, v180 op_sel_hi:[0,1,0]
	v_fma_mix_f32 v12, v7, v36, v12 op_sel:[0,1,0] op_sel_hi:[0,1,0]
	v_fma_mix_f32 v12, v8, v37, v12 op_sel_hi:[0,1,0]
	v_fma_mix_f32 v12, v9, v37, v12 op_sel:[0,1,0] op_sel_hi:[0,1,0]
	v_fma_mix_f32 v122, v6, v22, v180 op_sel_hi:[0,1,0]
	v_fma_mix_f32 v122, v7, v22, v122 op_sel:[0,1,0] op_sel_hi:[0,1,0]
	v_add_f32_dpp v12, v12, v12 row_ror:1 row_mask:0xf bank_mask:0xf bound_ctrl:1
	v_fma_mix_f32 v122, v8, v23, v122 op_sel_hi:[0,1,0]
	v_fma_mix_f32 v122, v9, v23, v122 op_sel:[0,1,0] op_sel_hi:[0,1,0]
	v_add_f32_dpp v12, v12, v12 row_ror:2 row_mask:0xf bank_mask:0xf bound_ctrl:1
	v_pk_fma_f32 v[48:49], v[44:45], v[66:67], v[6:7] op_sel:[0,1,0]
	v_pk_fma_f32 v[50:51], v[46:47], v[66:67], v[8:9] op_sel:[0,1,0]
	v_add_f32_dpp v12, v12, v12 row_ror:4 row_mask:0xf bank_mask:0xf bound_ctrl:1
	v_add_f32_dpp v83, v83, v83 row_ror:8 row_mask:0xf bank_mask:0xc
	v_add_f32_dpp v83, v52, v52 row_ror:8 row_mask:0xf bank_mask:0x3
	v_add_f32_dpp v100, v100, v100 row_ror:8 row_mask:0xf bank_mask:0xc
	v_add_f32_dpp v12, v12, v12 row_ror:8 row_mask:0xf bank_mask:0xf bound_ctrl:1
	v_pk_fma_f32 v[6:7], v[40:41], v[12:13], v[48:49] op_sel_hi:[1,0,1] neg_lo:[1,0,0] neg_hi:[1,0,0]
	v_pk_fma_f32 v[8:9], v[42:43], v[12:13], v[50:51] op_sel_hi:[1,0,1] neg_lo:[1,0,0] neg_hi:[1,0,0]
	s_waitcnt lgkmcnt(1)
	ds_read_b128 v[20:23], v10 offset:20736
	ds_read_b128 v[28:31], v10 offset:21248
	ds_read_b128 v[24:27], v10 offset:20992
	v_fma_mix_f32 v12, v6, v88, v180 op_sel_hi:[0,1,0]
	v_fma_mix_f32 v12, v7, v88, v12 op_sel:[0,1,0] op_sel_hi:[0,1,0]
	v_fma_mix_f32 v12, v8, v89, v12 op_sel_hi:[0,1,0]
	v_fma_mix_f32 v12, v9, v89, v12 op_sel:[0,1,0] op_sel_hi:[0,1,0]
	v_fma_mix_f32 v123, v6, v38, v180 op_sel_hi:[0,1,0]
	v_fma_mix_f32 v123, v7, v38, v123 op_sel:[0,1,0] op_sel_hi:[0,1,0]
	v_add_f32_dpp v12, v12, v12 row_ror:1 row_mask:0xf bank_mask:0xf bound_ctrl:1
	v_fma_mix_f32 v123, v8, v39, v123 op_sel_hi:[0,1,0]
	v_fma_mix_f32 v123, v9, v39, v123 op_sel:[0,1,0] op_sel_hi:[0,1,0]
	v_add_f32_dpp v12, v12, v12 row_ror:2 row_mask:0xf bank_mask:0xf bound_ctrl:1
	v_pk_fma_f32 v[48:49], v[96:97], v[68:69], v[6:7] op_sel_hi:[1,0,1]
	v_pk_fma_f32 v[50:51], v[98:99], v[68:69], v[8:9] op_sel_hi:[1,0,1]
	v_add_f32_dpp v12, v12, v12 row_ror:4 row_mask:0xf bank_mask:0xf bound_ctrl:1
	v_add_f32_dpp v100, v53, v53 row_ror:8 row_mask:0xf bank_mask:0x3
	v_add_f32_dpp v101, v101, v101 row_ror:8 row_mask:0xf bank_mask:0xc
	v_add_f32_dpp v101, v54, v54 row_ror:8 row_mask:0xf bank_mask:0x3
	v_add_f32_dpp v12, v12, v12 row_ror:8 row_mask:0xf bank_mask:0xf bound_ctrl:1
	v_pk_fma_f32 v[6:7], v[92:93], v[12:13], v[48:49] op_sel_hi:[1,0,1] neg_lo:[1,0,0] neg_hi:[1,0,0]
	v_pk_fma_f32 v[8:9], v[94:95], v[12:13], v[50:51] op_sel_hi:[1,0,1] neg_lo:[1,0,0] neg_hi:[1,0,0]
	ds_read_b128 v[36:39], v10 offset:21760
	ds_read_b128 v[44:47], v10 offset:22272
	ds_read_b128 v[40:43], v10 offset:22016
	v_fma_mix_f32 v12, v6, v110, v180 op_sel_hi:[0,1,0]
	v_fma_mix_f32 v12, v7, v110, v12 op_sel:[0,1,0] op_sel_hi:[0,1,0]
	v_fma_mix_f32 v12, v8, v111, v12 op_sel_hi:[0,1,0]
	v_fma_mix_f32 v12, v9, v111, v12 op_sel:[0,1,0] op_sel_hi:[0,1,0]
	v_fma_mix_f32 v124, v6, v90, v180 op_sel_hi:[0,1,0]
	v_fma_mix_f32 v124, v7, v90, v124 op_sel:[0,1,0] op_sel_hi:[0,1,0]
	v_add_f32_dpp v12, v12, v12 row_ror:1 row_mask:0xf bank_mask:0xf bound_ctrl:1
	v_fma_mix_f32 v124, v8, v91, v124 op_sel_hi:[0,1,0]
	v_fma_mix_f32 v124, v9, v91, v124 op_sel:[0,1,0] op_sel_hi:[0,1,0]
	v_add_f32_dpp v12, v12, v12 row_ror:2 row_mask:0xf bank_mask:0xf bound_ctrl:1
	v_pk_fma_f32 v[48:49], v[118:119], v[68:69], v[6:7] op_sel:[0,1,0]
	v_pk_fma_f32 v[50:51], v[120:121], v[68:69], v[8:9] op_sel:[0,1,0]
	v_add_f32_dpp v12, v12, v12 row_ror:4 row_mask:0xf bank_mask:0xf bound_ctrl:1
	v_add_f32_dpp v102, v102, v102 row_ror:8 row_mask:0xf bank_mask:0xc
	v_add_f32_dpp v102, v55, v55 row_ror:8 row_mask:0xf bank_mask:0x3
	v_add_f32_dpp v103, v103, v103 row_ror:8 row_mask:0xf bank_mask:0xc
	v_add_f32_dpp v12, v12, v12 row_ror:8 row_mask:0xf bank_mask:0xf bound_ctrl:1
	v_pk_fma_f32 v[6:7], v[114:115], v[12:13], v[48:49] op_sel_hi:[1,0,1] neg_lo:[1,0,0] neg_hi:[1,0,0]
	v_pk_fma_f32 v[8:9], v[116:117], v[12:13], v[50:51] op_sel_hi:[1,0,1] neg_lo:[1,0,0] neg_hi:[1,0,0]
	v_pk_mul_f32 v[6:7], v[6:7], v[106:107]
	v_pk_mul_f32 v[8:9], v[8:9], v[108:109]
	s_waitcnt lgkmcnt(0)
	ds_read_b128 v[88:91], v10 offset:22784
	ds_read_b128 v[96:99], v10 offset:23296
	ds_read_b128 v[92:95], v10 offset:23040
	v_fma_mix_f32 v12, v6, v20, v180 op_sel_hi:[0,1,0]
	v_fma_mix_f32 v12, v7, v20, v12 op_sel:[0,1,0] op_sel_hi:[0,1,0]
	v_fma_mix_f32 v12, v8, v21, v12 op_sel_hi:[0,1,0]
	v_fma_mix_f32 v12, v9, v21, v12 op_sel:[0,1,0] op_sel_hi:[0,1,0]
	v_fma_mix_f32 v125, v6, v112, v180 op_sel_hi:[0,1,0]
	v_fma_mix_f32 v125, v7, v112, v125 op_sel:[0,1,0] op_sel_hi:[0,1,0]
	v_add_f32_dpp v12, v12, v12 row_ror:1 row_mask:0xf bank_mask:0xf bound_ctrl:1
	v_fma_mix_f32 v125, v8, v113, v125 op_sel_hi:[0,1,0]
	v_fma_mix_f32 v125, v9, v113, v125 op_sel:[0,1,0] op_sel_hi:[0,1,0]
	v_add_f32_dpp v12, v12, v12 row_ror:2 row_mask:0xf bank_mask:0xf bound_ctrl:1
	v_pk_fma_f32 v[48:49], v[28:29], v[70:71], v[6:7] op_sel_hi:[1,0,1]
	v_pk_fma_f32 v[50:51], v[30:31], v[70:71], v[8:9] op_sel_hi:[1,0,1]
	v_add_f32_dpp v12, v12, v12 row_ror:4 row_mask:0xf bank_mask:0xf bound_ctrl:1
	v_add_f32_dpp v103, v56, v56 row_ror:8 row_mask:0xf bank_mask:0x3
	v_add_f32_dpp v104, v104, v104 row_ror:8 row_mask:0xf bank_mask:0xc
	v_add_f32_dpp v104, v57, v57 row_ror:8 row_mask:0xf bank_mask:0x3
	v_add_f32_dpp v12, v12, v12 row_ror:8 row_mask:0xf bank_mask:0xf bound_ctrl:1
	v_pk_fma_f32 v[6:7], v[24:25], v[12:13], v[48:49] op_sel_hi:[1,0,1] neg_lo:[1,0,0] neg_hi:[1,0,0]
	v_pk_fma_f32 v[8:9], v[26:27], v[12:13], v[50:51] op_sel_hi:[1,0,1] neg_lo:[1,0,0] neg_hi:[1,0,0]
	ds_read_b128 v[110:113], v10 offset:23808
	ds_read_b128 v[106:109], v10 offset:23552
	ds_read_b128 v[118:121], v10 offset:24320
	ds_read_b128 v[114:117], v10 offset:24064
	ds_read_b128 v[66:69], v11 offset:1536
	v_fma_mix_f32 v12, v6, v36, v180 op_sel_hi:[0,1,0]
	v_fma_mix_f32 v12, v7, v36, v12 op_sel:[0,1,0] op_sel_hi:[0,1,0]
	v_fma_mix_f32 v12, v8, v37, v12 op_sel_hi:[0,1,0]
	v_fma_mix_f32 v12, v9, v37, v12 op_sel:[0,1,0] op_sel_hi:[0,1,0]
	v_fma_mix_f32 v126, v6, v22, v180 op_sel_hi:[0,1,0]
	v_fma_mix_f32 v126, v7, v22, v126 op_sel:[0,1,0] op_sel_hi:[0,1,0]
	v_add_f32_dpp v12, v12, v12 row_ror:1 row_mask:0xf bank_mask:0xf bound_ctrl:1
	v_fma_mix_f32 v126, v8, v23, v126 op_sel_hi:[0,1,0]
	v_fma_mix_f32 v126, v9, v23, v126 op_sel:[0,1,0] op_sel_hi:[0,1,0]
	v_add_f32_dpp v12, v12, v12 row_ror:2 row_mask:0xf bank_mask:0xf bound_ctrl:1
	v_pk_fma_f32 v[48:49], v[44:45], v[70:71], v[6:7] op_sel:[0,1,0]
	v_pk_fma_f32 v[50:51], v[46:47], v[70:71], v[8:9] op_sel:[0,1,0]
	v_add_f32_dpp v12, v12, v12 row_ror:4 row_mask:0xf bank_mask:0xf bound_ctrl:1
	v_add_f32_dpp v105, v105, v105 row_ror:8 row_mask:0xf bank_mask:0xc
	v_add_f32_dpp v105, v81, v81 row_ror:8 row_mask:0xf bank_mask:0x3
	v_add_f32_dpp v12, v12, v12 row_ror:8 row_mask:0xf bank_mask:0xf bound_ctrl:1
	v_pk_fma_f32 v[6:7], v[40:41], v[12:13], v[48:49] op_sel_hi:[1,0,1] neg_lo:[1,0,0] neg_hi:[1,0,0]
	v_pk_fma_f32 v[8:9], v[42:43], v[12:13], v[50:51] op_sel_hi:[1,0,1] neg_lo:[1,0,0] neg_hi:[1,0,0]
	s_waitcnt lgkmcnt(1)
	ds_read_b128 v[20:23], v10 offset:24832
	ds_read_b128 v[28:31], v10 offset:25344
	ds_read_b128 v[24:27], v10 offset:25088
	v_fma_mix_f32 v12, v6, v88, v180 op_sel_hi:[0,1,0]
	v_fma_mix_f32 v12, v7, v88, v12 op_sel:[0,1,0] op_sel_hi:[0,1,0]
	v_fma_mix_f32 v12, v8, v89, v12 op_sel_hi:[0,1,0]
	v_fma_mix_f32 v12, v9, v89, v12 op_sel:[0,1,0] op_sel_hi:[0,1,0]
	v_fma_mix_f32 v127, v6, v38, v180 op_sel_hi:[0,1,0]
	v_fma_mix_f32 v127, v7, v38, v127 op_sel:[0,1,0] op_sel_hi:[0,1,0]
	v_add_f32_dpp v12, v12, v12 row_ror:1 row_mask:0xf bank_mask:0xf bound_ctrl:1
	v_fma_mix_f32 v127, v8, v39, v127 op_sel_hi:[0,1,0]
	v_fma_mix_f32 v127, v9, v39, v127 op_sel:[0,1,0] op_sel_hi:[0,1,0]
	v_add_f32_dpp v12, v12, v12 row_ror:2 row_mask:0xf bank_mask:0xf bound_ctrl:1
	v_pk_fma_f32 v[48:49], v[96:97], v[72:73], v[6:7] op_sel_hi:[1,0,1]
	v_pk_fma_f32 v[50:51], v[98:99], v[72:73], v[8:9] op_sel_hi:[1,0,1]
	v_add_f32_dpp v12, v12, v12 row_ror:4 row_mask:0xf bank_mask:0xf bound_ctrl:1
	v_add_f32_dpp v61, v61, v61 row_ror:8 row_mask:0xf bank_mask:0xc
	v_add_f32_dpp v61, v82, v82 row_ror:8 row_mask:0xf bank_mask:0x3
	v_add_f32_dpp v12, v12, v12 row_ror:8 row_mask:0xf bank_mask:0xf bound_ctrl:1
	v_pk_fma_f32 v[6:7], v[92:93], v[12:13], v[48:49] op_sel_hi:[1,0,1] neg_lo:[1,0,0] neg_hi:[1,0,0]
	v_pk_fma_f32 v[8:9], v[94:95], v[12:13], v[50:51] op_sel_hi:[1,0,1] neg_lo:[1,0,0] neg_hi:[1,0,0]
	ds_read_b128 v[36:39], v10 offset:25856
	ds_read_b128 v[44:47], v10 offset:26368
	ds_read_b128 v[40:43], v10 offset:26112
	v_fma_mix_f32 v12, v6, v110, v180 op_sel_hi:[0,1,0]
	v_fma_mix_f32 v12, v7, v110, v12 op_sel:[0,1,0] op_sel_hi:[0,1,0]
	v_fma_mix_f32 v12, v8, v111, v12 op_sel_hi:[0,1,0]
	v_fma_mix_f32 v12, v9, v111, v12 op_sel:[0,1,0] op_sel_hi:[0,1,0]
	v_fma_mix_f32 v128, v6, v90, v180 op_sel_hi:[0,1,0]
	v_fma_mix_f32 v128, v7, v90, v128 op_sel:[0,1,0] op_sel_hi:[0,1,0]
	v_add_f32_dpp v12, v12, v12 row_ror:1 row_mask:0xf bank_mask:0xf bound_ctrl:1
	v_fma_mix_f32 v128, v8, v91, v128 op_sel_hi:[0,1,0]
	v_fma_mix_f32 v128, v9, v91, v128 op_sel:[0,1,0] op_sel_hi:[0,1,0]
	v_add_f32_dpp v12, v12, v12 row_ror:2 row_mask:0xf bank_mask:0xf bound_ctrl:1
	v_pk_fma_f32 v[48:49], v[118:119], v[72:73], v[6:7] op_sel:[0,1,0]
	v_pk_fma_f32 v[50:51], v[120:121], v[72:73], v[8:9] op_sel:[0,1,0]
	v_add_f32_dpp v12, v12, v12 row_ror:4 row_mask:0xf bank_mask:0xf bound_ctrl:1
	v_add_f32_dpp v103, v103, v103 row_ror:4 row_mask:0xf bank_mask:0xa
	v_add_f32_dpp v103, v83, v83 row_ror:12 row_mask:0xf bank_mask:0x5
	v_add_f32_dpp v104, v104, v104 row_ror:4 row_mask:0xf bank_mask:0xa
	v_add_f32_dpp v12, v12, v12 row_ror:8 row_mask:0xf bank_mask:0xf bound_ctrl:1
	v_pk_fma_f32 v[6:7], v[114:115], v[12:13], v[48:49] op_sel_hi:[1,0,1] neg_lo:[1,0,0] neg_hi:[1,0,0]
	v_pk_fma_f32 v[8:9], v[116:117], v[12:13], v[50:51] op_sel_hi:[1,0,1] neg_lo:[1,0,0] neg_hi:[1,0,0]
	v_pk_mul_f32 v[6:7], v[6:7], v[106:107]
	v_pk_mul_f32 v[8:9], v[8:9], v[108:109]
	s_waitcnt lgkmcnt(0)
	ds_read_b128 v[88:91], v10 offset:26880
	ds_read_b128 v[96:99], v10 offset:27392
	ds_read_b128 v[92:95], v10 offset:27136
	v_fma_mix_f32 v12, v6, v20, v180 op_sel_hi:[0,1,0]
	v_fma_mix_f32 v12, v7, v20, v12 op_sel:[0,1,0] op_sel_hi:[0,1,0]
	v_fma_mix_f32 v12, v8, v21, v12 op_sel_hi:[0,1,0]
	v_fma_mix_f32 v12, v9, v21, v12 op_sel:[0,1,0] op_sel_hi:[0,1,0]
	v_fma_mix_f32 v129, v6, v112, v180 op_sel_hi:[0,1,0]
	v_fma_mix_f32 v129, v7, v112, v129 op_sel:[0,1,0] op_sel_hi:[0,1,0]
	v_add_f32_dpp v12, v12, v12 row_ror:1 row_mask:0xf bank_mask:0xf bound_ctrl:1
	v_fma_mix_f32 v129, v8, v113, v129 op_sel_hi:[0,1,0]
	v_fma_mix_f32 v129, v9, v113, v129 op_sel:[0,1,0] op_sel_hi:[0,1,0]
	v_add_f32_dpp v12, v12, v12 row_ror:2 row_mask:0xf bank_mask:0xf bound_ctrl:1
	v_pk_fma_f32 v[48:49], v[28:29], v[66:67], v[6:7] op_sel_hi:[1,0,1]
	v_pk_fma_f32 v[50:51], v[30:31], v[66:67], v[8:9] op_sel_hi:[1,0,1]
	v_add_f32_dpp v12, v12, v12 row_ror:4 row_mask:0xf bank_mask:0xf bound_ctrl:1
	v_add_f32_dpp v104, v100, v100 row_ror:12 row_mask:0xf bank_mask:0x5
	v_add_f32_dpp v105, v105, v105 row_ror:4 row_mask:0xf bank_mask:0xa
	v_add_f32_dpp v105, v101, v101 row_ror:12 row_mask:0xf bank_mask:0x5
	v_add_f32_dpp v12, v12, v12 row_ror:8 row_mask:0xf bank_mask:0xf bound_ctrl:1
	v_pk_fma_f32 v[6:7], v[24:25], v[12:13], v[48:49] op_sel_hi:[1,0,1] neg_lo:[1,0,0] neg_hi:[1,0,0]
	v_pk_fma_f32 v[8:9], v[26:27], v[12:13], v[50:51] op_sel_hi:[1,0,1] neg_lo:[1,0,0] neg_hi:[1,0,0]
	ds_read_b128 v[110:113], v10 offset:27904
	ds_read_b128 v[106:109], v10 offset:27648
	ds_read_b128 v[118:121], v10 offset:28416
	ds_read_b128 v[114:117], v10 offset:28160
	ds_read_b128 v[70:73], v11 offset:1792
	v_fma_mix_f32 v12, v6, v36, v180 op_sel_hi:[0,1,0]
	v_fma_mix_f32 v12, v7, v36, v12 op_sel:[0,1,0] op_sel_hi:[0,1,0]
	v_fma_mix_f32 v12, v8, v37, v12 op_sel_hi:[0,1,0]
	v_fma_mix_f32 v12, v9, v37, v12 op_sel:[0,1,0] op_sel_hi:[0,1,0]
	v_fma_mix_f32 v130, v6, v22, v180 op_sel_hi:[0,1,0]
	v_fma_mix_f32 v130, v7, v22, v130 op_sel:[0,1,0] op_sel_hi:[0,1,0]
	v_add_f32_dpp v12, v12, v12 row_ror:1 row_mask:0xf bank_mask:0xf bound_ctrl:1
	v_fma_mix_f32 v130, v8, v23, v130 op_sel_hi:[0,1,0]
	v_fma_mix_f32 v130, v9, v23, v130 op_sel:[0,1,0] op_sel_hi:[0,1,0]
	v_add_f32_dpp v12, v12, v12 row_ror:2 row_mask:0xf bank_mask:0xf bound_ctrl:1
	v_pk_fma_f32 v[48:49], v[44:45], v[66:67], v[6:7] op_sel:[0,1,0]
	v_pk_fma_f32 v[50:51], v[46:47], v[66:67], v[8:9] op_sel:[0,1,0]
	v_add_f32_dpp v12, v12, v12 row_ror:4 row_mask:0xf bank_mask:0xf bound_ctrl:1
	v_add_f32_dpp v61, v61, v61 row_ror:4 row_mask:0xf bank_mask:0xa
	v_add_f32_dpp v61, v102, v102 row_ror:12 row_mask:0xf bank_mask:0x5
	v_add_f32_dpp v12, v12, v12 row_ror:8 row_mask:0xf bank_mask:0xf bound_ctrl:1
	v_pk_fma_f32 v[6:7], v[40:41], v[12:13], v[48:49] op_sel_hi:[1,0,1] neg_lo:[1,0,0] neg_hi:[1,0,0]
	v_pk_fma_f32 v[8:9], v[42:43], v[12:13], v[50:51] op_sel_hi:[1,0,1] neg_lo:[1,0,0] neg_hi:[1,0,0]
	s_waitcnt lgkmcnt(1)
	ds_read_b128 v[20:23], v10 offset:28928
	ds_read_b128 v[28:31], v10 offset:29440
	ds_read_b128 v[24:27], v10 offset:29184
	v_fma_mix_f32 v12, v6, v88, v180 op_sel_hi:[0,1,0]
	v_fma_mix_f32 v12, v7, v88, v12 op_sel:[0,1,0] op_sel_hi:[0,1,0]
	v_fma_mix_f32 v12, v8, v89, v12 op_sel_hi:[0,1,0]
	v_fma_mix_f32 v12, v9, v89, v12 op_sel:[0,1,0] op_sel_hi:[0,1,0]
	v_fma_mix_f32 v131, v6, v38, v180 op_sel_hi:[0,1,0]
	v_fma_mix_f32 v131, v7, v38, v131 op_sel:[0,1,0] op_sel_hi:[0,1,0]
	v_add_f32_dpp v12, v12, v12 row_ror:1 row_mask:0xf bank_mask:0xf bound_ctrl:1
	v_fma_mix_f32 v131, v8, v39, v131 op_sel_hi:[0,1,0]
	v_fma_mix_f32 v131, v9, v39, v131 op_sel:[0,1,0] op_sel_hi:[0,1,0]
	v_add_f32_dpp v12, v12, v12 row_ror:2 row_mask:0xf bank_mask:0xf bound_ctrl:1
	v_pk_fma_f32 v[48:49], v[96:97], v[68:69], v[6:7] op_sel_hi:[1,0,1]
	v_pk_fma_f32 v[50:51], v[98:99], v[68:69], v[8:9] op_sel_hi:[1,0,1]
	v_add_f32_dpp v12, v12, v12 row_ror:4 row_mask:0xf bank_mask:0xf bound_ctrl:1
	v_cndmask_b32_e64 v62, v105, v103, s[38:39]
	v_cndmask_b32_e64 v63, v103, v105, s[38:39]
	v_add_f32_dpp v12, v12, v12 row_ror:8 row_mask:0xf bank_mask:0xf bound_ctrl:1
	v_pk_fma_f32 v[6:7], v[92:93], v[12:13], v[48:49] op_sel_hi:[1,0,1] neg_lo:[1,0,0] neg_hi:[1,0,0]
	v_pk_fma_f32 v[8:9], v[94:95], v[12:13], v[50:51] op_sel_hi:[1,0,1] neg_lo:[1,0,0] neg_hi:[1,0,0]
	ds_read_b128 v[36:39], v10 offset:29952
	ds_read_b128 v[44:47], v10 offset:30464
	ds_read_b128 v[40:43], v10 offset:30208
	v_fma_mix_f32 v12, v6, v110, v180 op_sel_hi:[0,1,0]
	v_fma_mix_f32 v12, v7, v110, v12 op_sel:[0,1,0] op_sel_hi:[0,1,0]
	v_fma_mix_f32 v12, v8, v111, v12 op_sel_hi:[0,1,0]
	v_fma_mix_f32 v12, v9, v111, v12 op_sel:[0,1,0] op_sel_hi:[0,1,0]
	v_fma_mix_f32 v132, v6, v90, v180 op_sel_hi:[0,1,0]
	v_fma_mix_f32 v132, v7, v90, v132 op_sel:[0,1,0] op_sel_hi:[0,1,0]
	v_add_f32_dpp v12, v12, v12 row_ror:1 row_mask:0xf bank_mask:0xf bound_ctrl:1
	v_fma_mix_f32 v132, v8, v91, v132 op_sel_hi:[0,1,0]
	v_fma_mix_f32 v132, v9, v91, v132 op_sel:[0,1,0] op_sel_hi:[0,1,0]
	v_add_f32_dpp v12, v12, v12 row_ror:2 row_mask:0xf bank_mask:0xf bound_ctrl:1
	v_pk_fma_f32 v[48:49], v[118:119], v[68:69], v[6:7] op_sel:[0,1,0]
	v_pk_fma_f32 v[50:51], v[120:121], v[68:69], v[8:9] op_sel:[0,1,0]
	v_add_f32_dpp v12, v12, v12 row_ror:4 row_mask:0xf bank_mask:0xf bound_ctrl:1
	v_cndmask_b32_e64 v64, v61, v104, s[38:39]
	v_cndmask_b32_e64 v65, v104, v61, s[38:39]
	v_add_f32_dpp v12, v12, v12 row_ror:8 row_mask:0xf bank_mask:0xf bound_ctrl:1
	v_pk_fma_f32 v[6:7], v[114:115], v[12:13], v[48:49] op_sel_hi:[1,0,1] neg_lo:[1,0,0] neg_hi:[1,0,0]
	v_pk_fma_f32 v[8:9], v[116:117], v[12:13], v[50:51] op_sel_hi:[1,0,1] neg_lo:[1,0,0] neg_hi:[1,0,0]
	v_pk_mul_f32 v[6:7], v[6:7], v[106:107]
	v_pk_mul_f32 v[8:9], v[8:9], v[108:109]
	s_waitcnt lgkmcnt(0)
	ds_read_b128 v[88:91], v10 offset:30976
	ds_read_b128 v[96:99], v10 offset:31488
	ds_read_b128 v[92:95], v10 offset:31232
	v_fma_mix_f32 v12, v6, v20, v180 op_sel_hi:[0,1,0]
	v_fma_mix_f32 v12, v7, v20, v12 op_sel:[0,1,0] op_sel_hi:[0,1,0]
	v_fma_mix_f32 v12, v8, v21, v12 op_sel_hi:[0,1,0]
	v_fma_mix_f32 v12, v9, v21, v12 op_sel:[0,1,0] op_sel_hi:[0,1,0]
	v_fma_mix_f32 v133, v6, v112, v180 op_sel_hi:[0,1,0]
	v_fma_mix_f32 v133, v7, v112, v133 op_sel:[0,1,0] op_sel_hi:[0,1,0]
	v_add_f32_dpp v12, v12, v12 row_ror:1 row_mask:0xf bank_mask:0xf bound_ctrl:1
	v_fma_mix_f32 v133, v8, v113, v133 op_sel_hi:[0,1,0]
	v_fma_mix_f32 v133, v9, v113, v133 op_sel:[0,1,0] op_sel_hi:[0,1,0]
	v_add_f32_dpp v12, v12, v12 row_ror:2 row_mask:0xf bank_mask:0xf bound_ctrl:1
	v_pk_fma_f32 v[48:49], v[28:29], v[70:71], v[6:7] op_sel_hi:[1,0,1]
	v_pk_fma_f32 v[50:51], v[30:31], v[70:71], v[8:9] op_sel_hi:[1,0,1]
	v_add_f32_dpp v12, v12, v12 row_ror:4 row_mask:0xf bank_mask:0xf bound_ctrl:1
	v_add_f32_dpp v62, v63, v62 quad_perm:[2,3,0,1] row_mask:0xf bank_mask:0xf bound_ctrl:1
	v_add_f32_dpp v63, v65, v64 quad_perm:[2,3,0,1] row_mask:0xf bank_mask:0xf bound_ctrl:1
	v_add_f32_dpp v12, v12, v12 row_ror:8 row_mask:0xf bank_mask:0xf bound_ctrl:1
	v_pk_fma_f32 v[6:7], v[24:25], v[12:13], v[48:49] op_sel_hi:[1,0,1] neg_lo:[1,0,0] neg_hi:[1,0,0]
	v_pk_fma_f32 v[8:9], v[26:27], v[12:13], v[50:51] op_sel_hi:[1,0,1] neg_lo:[1,0,0] neg_hi:[1,0,0]
	ds_read_b128 v[110:113], v10 offset:32000
	ds_read_b128 v[106:109], v10 offset:31744
	ds_read_b128 v[118:121], v10 offset:32512
	ds_read_b128 v[114:117], v10 offset:32256
	ds_read_b128 v[66:69], v11 offset:2048
	v_fma_mix_f32 v12, v6, v36, v180 op_sel_hi:[0,1,0]
	v_fma_mix_f32 v12, v7, v36, v12 op_sel:[0,1,0] op_sel_hi:[0,1,0]
	v_fma_mix_f32 v12, v8, v37, v12 op_sel_hi:[0,1,0]
	v_fma_mix_f32 v12, v9, v37, v12 op_sel:[0,1,0] op_sel_hi:[0,1,0]
	v_fma_mix_f32 v134, v6, v22, v180 op_sel_hi:[0,1,0]
	v_fma_mix_f32 v134, v7, v22, v134 op_sel:[0,1,0] op_sel_hi:[0,1,0]
	v_add_f32_dpp v12, v12, v12 row_ror:1 row_mask:0xf bank_mask:0xf bound_ctrl:1
	v_fma_mix_f32 v134, v8, v23, v134 op_sel_hi:[0,1,0]
	v_fma_mix_f32 v134, v9, v23, v134 op_sel:[0,1,0] op_sel_hi:[0,1,0]
	v_add_f32_dpp v12, v12, v12 row_ror:2 row_mask:0xf bank_mask:0xf bound_ctrl:1
	v_pk_fma_f32 v[48:49], v[44:45], v[70:71], v[6:7] op_sel:[0,1,0]
	v_pk_fma_f32 v[50:51], v[46:47], v[70:71], v[8:9] op_sel:[0,1,0]
	v_add_f32_dpp v12, v12, v12 row_ror:4 row_mask:0xf bank_mask:0xf bound_ctrl:1
	v_cndmask_b32_e64 v65, v63, v62, s[40:41]
	v_cndmask_b32_e64 v62, v62, v63, s[40:41]
	v_add_f32_dpp v12, v12, v12 row_ror:8 row_mask:0xf bank_mask:0xf bound_ctrl:1
	v_pk_fma_f32 v[6:7], v[40:41], v[12:13], v[48:49] op_sel_hi:[1,0,1] neg_lo:[1,0,0] neg_hi:[1,0,0]
	v_pk_fma_f32 v[8:9], v[42:43], v[12:13], v[50:51] op_sel_hi:[1,0,1] neg_lo:[1,0,0] neg_hi:[1,0,0]
	s_waitcnt lgkmcnt(1)
	ds_read_b128 v[20:23], v10 offset:33024
	ds_read_b128 v[28:31], v10 offset:33536
	ds_read_b128 v[24:27], v10 offset:33280
	v_fma_mix_f32 v12, v6, v88, v180 op_sel_hi:[0,1,0]
	v_fma_mix_f32 v12, v7, v88, v12 op_sel:[0,1,0] op_sel_hi:[0,1,0]
	v_fma_mix_f32 v12, v8, v89, v12 op_sel_hi:[0,1,0]
	v_fma_mix_f32 v12, v9, v89, v12 op_sel:[0,1,0] op_sel_hi:[0,1,0]
	v_fma_mix_f32 v135, v6, v38, v180 op_sel_hi:[0,1,0]
	v_fma_mix_f32 v135, v7, v38, v135 op_sel:[0,1,0] op_sel_hi:[0,1,0]
	v_add_f32_dpp v12, v12, v12 row_ror:1 row_mask:0xf bank_mask:0xf bound_ctrl:1
	v_fma_mix_f32 v135, v8, v39, v135 op_sel_hi:[0,1,0]
	v_fma_mix_f32 v135, v9, v39, v135 op_sel:[0,1,0] op_sel_hi:[0,1,0]
	v_add_f32_dpp v12, v12, v12 row_ror:2 row_mask:0xf bank_mask:0xf bound_ctrl:1
	v_pk_fma_f32 v[48:49], v[96:97], v[72:73], v[6:7] op_sel_hi:[1,0,1]
	v_pk_fma_f32 v[50:51], v[98:99], v[72:73], v[8:9] op_sel_hi:[1,0,1]
	v_add_f32_dpp v12, v12, v12 row_ror:4 row_mask:0xf bank_mask:0xf bound_ctrl:1
	v_add_f32_dpp v62, v62, v65 quad_perm:[1,0,3,2] row_mask:0xf bank_mask:0xf bound_ctrl:1
	v_cvt_pk_bf16_f32 v62, v62, v62
	v_add_f32_dpp v12, v12, v12 row_ror:8 row_mask:0xf bank_mask:0xf bound_ctrl:1
	v_pk_fma_f32 v[6:7], v[92:93], v[12:13], v[48:49] op_sel_hi:[1,0,1] neg_lo:[1,0,0] neg_hi:[1,0,0]
	v_pk_fma_f32 v[8:9], v[94:95], v[12:13], v[50:51] op_sel_hi:[1,0,1] neg_lo:[1,0,0] neg_hi:[1,0,0]
	ds_read_b128 v[36:39], v10 offset:34048
	ds_read_b128 v[44:47], v10 offset:34560
	ds_read_b128 v[40:43], v10 offset:34304
	v_fma_mix_f32 v12, v6, v110, v180 op_sel_hi:[0,1,0]
	v_fma_mix_f32 v12, v7, v110, v12 op_sel:[0,1,0] op_sel_hi:[0,1,0]
	v_fma_mix_f32 v12, v8, v111, v12 op_sel_hi:[0,1,0]
	v_fma_mix_f32 v12, v9, v111, v12 op_sel:[0,1,0] op_sel_hi:[0,1,0]
	v_fma_mix_f32 v136, v6, v90, v180 op_sel_hi:[0,1,0]
	v_fma_mix_f32 v136, v7, v90, v136 op_sel:[0,1,0] op_sel_hi:[0,1,0]
	v_add_f32_dpp v12, v12, v12 row_ror:1 row_mask:0xf bank_mask:0xf bound_ctrl:1
	v_fma_mix_f32 v136, v8, v91, v136 op_sel_hi:[0,1,0]
	v_fma_mix_f32 v136, v9, v91, v136 op_sel:[0,1,0] op_sel_hi:[0,1,0]
	v_add_f32_dpp v12, v12, v12 row_ror:2 row_mask:0xf bank_mask:0xf bound_ctrl:1
	v_pk_fma_f32 v[48:49], v[118:119], v[72:73], v[6:7] op_sel:[0,1,0]
	v_pk_fma_f32 v[50:51], v[120:121], v[72:73], v[8:9] op_sel:[0,1,0]
	v_add_f32_dpp v12, v12, v12 row_ror:4 row_mask:0xf bank_mask:0xf bound_ctrl:1
	global_store_short v[2:3], v62, off
	v_lshl_add_u64 v[2:3], v[2:3], 0, s[84:85]
	v_add_f32_dpp v12, v12, v12 row_ror:8 row_mask:0xf bank_mask:0xf bound_ctrl:1
	v_pk_fma_f32 v[6:7], v[114:115], v[12:13], v[48:49] op_sel_hi:[1,0,1] neg_lo:[1,0,0] neg_hi:[1,0,0]
	v_pk_fma_f32 v[8:9], v[116:117], v[12:13], v[50:51] op_sel_hi:[1,0,1] neg_lo:[1,0,0] neg_hi:[1,0,0]
	v_pk_mul_f32 v[6:7], v[6:7], v[106:107]
	v_pk_mul_f32 v[8:9], v[8:9], v[108:109]
	s_waitcnt lgkmcnt(0)
	ds_read_b128 v[88:91], v10 offset:35072
	ds_read_b128 v[96:99], v10 offset:35584
	ds_read_b128 v[92:95], v10 offset:35328
	v_fma_mix_f32 v12, v6, v20, v180 op_sel_hi:[0,1,0]
	v_fma_mix_f32 v12, v7, v20, v12 op_sel:[0,1,0] op_sel_hi:[0,1,0]
	v_fma_mix_f32 v12, v8, v21, v12 op_sel_hi:[0,1,0]
	v_fma_mix_f32 v12, v9, v21, v12 op_sel:[0,1,0] op_sel_hi:[0,1,0]
	v_fma_mix_f32 v137, v6, v112, v180 op_sel_hi:[0,1,0]
	v_fma_mix_f32 v137, v7, v112, v137 op_sel:[0,1,0] op_sel_hi:[0,1,0]
	v_add_f32_dpp v12, v12, v12 row_ror:1 row_mask:0xf bank_mask:0xf bound_ctrl:1
	v_fma_mix_f32 v137, v8, v113, v137 op_sel_hi:[0,1,0]
	v_fma_mix_f32 v137, v9, v113, v137 op_sel:[0,1,0] op_sel_hi:[0,1,0]
	v_add_f32_dpp v12, v12, v12 row_ror:2 row_mask:0xf bank_mask:0xf bound_ctrl:1
	v_pk_fma_f32 v[48:49], v[28:29], v[66:67], v[6:7] op_sel_hi:[1,0,1]
	v_pk_fma_f32 v[50:51], v[30:31], v[66:67], v[8:9] op_sel_hi:[1,0,1]
	v_add_f32_dpp v12, v12, v12 row_ror:4 row_mask:0xf bank_mask:0xf bound_ctrl:1
	s_nop 1
	v_add_f32_dpp v12, v12, v12 row_ror:8 row_mask:0xf bank_mask:0xf bound_ctrl:1
	v_pk_fma_f32 v[6:7], v[24:25], v[12:13], v[48:49] op_sel_hi:[1,0,1] neg_lo:[1,0,0] neg_hi:[1,0,0]
	v_pk_fma_f32 v[8:9], v[26:27], v[12:13], v[50:51] op_sel_hi:[1,0,1] neg_lo:[1,0,0] neg_hi:[1,0,0]
	ds_read_b128 v[110:113], v10 offset:36096
	ds_read_b128 v[106:109], v10 offset:35840
	ds_read_b128 v[118:121], v10 offset:36608
	ds_read_b128 v[114:117], v10 offset:36352
	ds_read_b128 v[70:73], v11 offset:2304
	v_fma_mix_f32 v12, v6, v36, v180 op_sel_hi:[0,1,0]
	v_fma_mix_f32 v12, v7, v36, v12 op_sel:[0,1,0] op_sel_hi:[0,1,0]
	v_fma_mix_f32 v12, v8, v37, v12 op_sel_hi:[0,1,0]
	v_fma_mix_f32 v12, v9, v37, v12 op_sel:[0,1,0] op_sel_hi:[0,1,0]
	v_fma_mix_f32 v52, v6, v22, v180 op_sel_hi:[0,1,0]
	v_fma_mix_f32 v52, v7, v22, v52 op_sel:[0,1,0] op_sel_hi:[0,1,0]
	v_add_f32_dpp v12, v12, v12 row_ror:1 row_mask:0xf bank_mask:0xf bound_ctrl:1
	v_fma_mix_f32 v52, v8, v23, v52 op_sel_hi:[0,1,0]
	v_fma_mix_f32 v52, v9, v23, v52 op_sel:[0,1,0] op_sel_hi:[0,1,0]
	v_add_f32_dpp v12, v12, v12 row_ror:2 row_mask:0xf bank_mask:0xf bound_ctrl:1
	v_pk_fma_f32 v[48:49], v[44:45], v[66:67], v[6:7] op_sel:[0,1,0]
	v_pk_fma_f32 v[50:51], v[46:47], v[66:67], v[8:9] op_sel:[0,1,0]
	v_add_f32_dpp v12, v12, v12 row_ror:4 row_mask:0xf bank_mask:0xf bound_ctrl:1
	v_add_f32_dpp v130, v130, v130 row_ror:8 row_mask:0xf bank_mask:0xc
	v_add_f32_dpp v130, v122, v122 row_ror:8 row_mask:0xf bank_mask:0x3
	v_add_f32_dpp v131, v131, v131 row_ror:8 row_mask:0xf bank_mask:0xc
	v_add_f32_dpp v12, v12, v12 row_ror:8 row_mask:0xf bank_mask:0xf bound_ctrl:1
	v_pk_fma_f32 v[6:7], v[40:41], v[12:13], v[48:49] op_sel_hi:[1,0,1] neg_lo:[1,0,0] neg_hi:[1,0,0]
	v_pk_fma_f32 v[8:9], v[42:43], v[12:13], v[50:51] op_sel_hi:[1,0,1] neg_lo:[1,0,0] neg_hi:[1,0,0]
	s_waitcnt lgkmcnt(1)
	ds_read_b128 v[20:23], v10 offset:37120
	ds_read_b128 v[28:31], v10 offset:37632
	ds_read_b128 v[24:27], v10 offset:37376
	v_fma_mix_f32 v12, v6, v88, v180 op_sel_hi:[0,1,0]
	v_fma_mix_f32 v12, v7, v88, v12 op_sel:[0,1,0] op_sel_hi:[0,1,0]
	v_fma_mix_f32 v12, v8, v89, v12 op_sel_hi:[0,1,0]
	v_fma_mix_f32 v12, v9, v89, v12 op_sel:[0,1,0] op_sel_hi:[0,1,0]
	v_fma_mix_f32 v53, v6, v38, v180 op_sel_hi:[0,1,0]
	v_fma_mix_f32 v53, v7, v38, v53 op_sel:[0,1,0] op_sel_hi:[0,1,0]
	v_add_f32_dpp v12, v12, v12 row_ror:1 row_mask:0xf bank_mask:0xf bound_ctrl:1
	v_fma_mix_f32 v53, v8, v39, v53 op_sel_hi:[0,1,0]
	v_fma_mix_f32 v53, v9, v39, v53 op_sel:[0,1,0] op_sel_hi:[0,1,0]
	v_add_f32_dpp v12, v12, v12 row_ror:2 row_mask:0xf bank_mask:0xf bound_ctrl:1
	v_pk_fma_f32 v[48:49], v[96:97], v[68:69], v[6:7] op_sel_hi:[1,0,1]
	v_pk_fma_f32 v[50:51], v[98:99], v[68:69], v[8:9] op_sel_hi:[1,0,1]
	v_add_f32_dpp v12, v12, v12 row_ror:4 row_mask:0xf bank_mask:0xf bound_ctrl:1
	v_add_f32_dpp v131, v123, v123 row_ror:8 row_mask:0xf bank_mask:0x3
	v_add_f32_dpp v132, v132, v132 row_ror:8 row_mask:0xf bank_mask:0xc
	v_add_f32_dpp v132, v124, v124 row_ror:8 row_mask:0xf bank_mask:0x3
	v_add_f32_dpp v12, v12, v12 row_ror:8 row_mask:0xf bank_mask:0xf bound_ctrl:1
	v_pk_fma_f32 v[6:7], v[92:93], v[12:13], v[48:49] op_sel_hi:[1,0,1] neg_lo:[1,0,0] neg_hi:[1,0,0]
	v_pk_fma_f32 v[8:9], v[94:95], v[12:13], v[50:51] op_sel_hi:[1,0,1] neg_lo:[1,0,0] neg_hi:[1,0,0]
	ds_read_b128 v[36:39], v10 offset:38144
	ds_read_b128 v[44:47], v10 offset:38656
	ds_read_b128 v[40:43], v10 offset:38400
	v_fma_mix_f32 v12, v6, v110, v180 op_sel_hi:[0,1,0]
	v_fma_mix_f32 v12, v7, v110, v12 op_sel:[0,1,0] op_sel_hi:[0,1,0]
	v_fma_mix_f32 v12, v8, v111, v12 op_sel_hi:[0,1,0]
	v_fma_mix_f32 v12, v9, v111, v12 op_sel:[0,1,0] op_sel_hi:[0,1,0]
	v_fma_mix_f32 v54, v6, v90, v180 op_sel_hi:[0,1,0]
	v_fma_mix_f32 v54, v7, v90, v54 op_sel:[0,1,0] op_sel_hi:[0,1,0]
	v_add_f32_dpp v12, v12, v12 row_ror:1 row_mask:0xf bank_mask:0xf bound_ctrl:1
	v_fma_mix_f32 v54, v8, v91, v54 op_sel_hi:[0,1,0]
	v_fma_mix_f32 v54, v9, v91, v54 op_sel:[0,1,0] op_sel_hi:[0,1,0]
	v_add_f32_dpp v12, v12, v12 row_ror:2 row_mask:0xf bank_mask:0xf bound_ctrl:1
	v_pk_fma_f32 v[48:49], v[118:119], v[68:69], v[6:7] op_sel:[0,1,0]
	v_pk_fma_f32 v[50:51], v[120:121], v[68:69], v[8:9] op_sel:[0,1,0]
	v_add_f32_dpp v12, v12, v12 row_ror:4 row_mask:0xf bank_mask:0xf bound_ctrl:1
	v_add_f32_dpp v133, v133, v133 row_ror:8 row_mask:0xf bank_mask:0xc
	v_add_f32_dpp v133, v125, v125 row_ror:8 row_mask:0xf bank_mask:0x3
	v_add_f32_dpp v134, v134, v134 row_ror:8 row_mask:0xf bank_mask:0xc
	v_add_f32_dpp v12, v12, v12 row_ror:8 row_mask:0xf bank_mask:0xf bound_ctrl:1
	v_pk_fma_f32 v[6:7], v[114:115], v[12:13], v[48:49] op_sel_hi:[1,0,1] neg_lo:[1,0,0] neg_hi:[1,0,0]
	v_pk_fma_f32 v[8:9], v[116:117], v[12:13], v[50:51] op_sel_hi:[1,0,1] neg_lo:[1,0,0] neg_hi:[1,0,0]
	v_pk_mul_f32 v[6:7], v[6:7], v[106:107]
	v_pk_mul_f32 v[8:9], v[8:9], v[108:109]
	s_waitcnt lgkmcnt(0)
	ds_read_b128 v[88:91], v10 offset:39168
	ds_read_b128 v[96:99], v10 offset:39680
	ds_read_b128 v[92:95], v10 offset:39424
	v_fma_mix_f32 v12, v6, v20, v180 op_sel_hi:[0,1,0]
	v_fma_mix_f32 v12, v7, v20, v12 op_sel:[0,1,0] op_sel_hi:[0,1,0]
	v_fma_mix_f32 v12, v8, v21, v12 op_sel_hi:[0,1,0]
	v_fma_mix_f32 v12, v9, v21, v12 op_sel:[0,1,0] op_sel_hi:[0,1,0]
	v_fma_mix_f32 v55, v6, v112, v180 op_sel_hi:[0,1,0]
	v_fma_mix_f32 v55, v7, v112, v55 op_sel:[0,1,0] op_sel_hi:[0,1,0]
	v_add_f32_dpp v12, v12, v12 row_ror:1 row_mask:0xf bank_mask:0xf bound_ctrl:1
	v_fma_mix_f32 v55, v8, v113, v55 op_sel_hi:[0,1,0]
	v_fma_mix_f32 v55, v9, v113, v55 op_sel:[0,1,0] op_sel_hi:[0,1,0]
	v_add_f32_dpp v12, v12, v12 row_ror:2 row_mask:0xf bank_mask:0xf bound_ctrl:1
	v_pk_fma_f32 v[48:49], v[28:29], v[70:71], v[6:7] op_sel_hi:[1,0,1]
	v_pk_fma_f32 v[50:51], v[30:31], v[70:71], v[8:9] op_sel_hi:[1,0,1]
	v_add_f32_dpp v12, v12, v12 row_ror:4 row_mask:0xf bank_mask:0xf bound_ctrl:1
	v_add_f32_dpp v134, v126, v126 row_ror:8 row_mask:0xf bank_mask:0x3
	v_add_f32_dpp v135, v135, v135 row_ror:8 row_mask:0xf bank_mask:0xc
	v_add_f32_dpp v135, v127, v127 row_ror:8 row_mask:0xf bank_mask:0x3
	v_add_f32_dpp v12, v12, v12 row_ror:8 row_mask:0xf bank_mask:0xf bound_ctrl:1
	v_pk_fma_f32 v[6:7], v[24:25], v[12:13], v[48:49] op_sel_hi:[1,0,1] neg_lo:[1,0,0] neg_hi:[1,0,0]
	v_pk_fma_f32 v[8:9], v[26:27], v[12:13], v[50:51] op_sel_hi:[1,0,1] neg_lo:[1,0,0] neg_hi:[1,0,0]
	ds_read_b128 v[110:113], v10 offset:40192
	ds_read_b128 v[106:109], v10 offset:39936
	ds_read_b128 v[118:121], v10 offset:40704
	ds_read_b128 v[114:117], v10 offset:40448
	ds_read_b128 v[66:69], v11 offset:2560
	v_fma_mix_f32 v12, v6, v36, v180 op_sel_hi:[0,1,0]
	v_fma_mix_f32 v12, v7, v36, v12 op_sel:[0,1,0] op_sel_hi:[0,1,0]
	v_fma_mix_f32 v12, v8, v37, v12 op_sel_hi:[0,1,0]
	v_fma_mix_f32 v12, v9, v37, v12 op_sel:[0,1,0] op_sel_hi:[0,1,0]
	v_fma_mix_f32 v56, v6, v22, v180 op_sel_hi:[0,1,0]
	v_fma_mix_f32 v56, v7, v22, v56 op_sel:[0,1,0] op_sel_hi:[0,1,0]
	v_add_f32_dpp v12, v12, v12 row_ror:1 row_mask:0xf bank_mask:0xf bound_ctrl:1
	v_fma_mix_f32 v56, v8, v23, v56 op_sel_hi:[0,1,0]
	v_fma_mix_f32 v56, v9, v23, v56 op_sel:[0,1,0] op_sel_hi:[0,1,0]
	v_add_f32_dpp v12, v12, v12 row_ror:2 row_mask:0xf bank_mask:0xf bound_ctrl:1
	v_pk_fma_f32 v[48:49], v[44:45], v[70:71], v[6:7] op_sel:[0,1,0]
	v_pk_fma_f32 v[50:51], v[46:47], v[70:71], v[8:9] op_sel:[0,1,0]
	v_add_f32_dpp v12, v12, v12 row_ror:4 row_mask:0xf bank_mask:0xf bound_ctrl:1
	v_add_f32_dpp v136, v136, v136 row_ror:8 row_mask:0xf bank_mask:0xc
	v_add_f32_dpp v136, v128, v128 row_ror:8 row_mask:0xf bank_mask:0x3
	v_add_f32_dpp v12, v12, v12 row_ror:8 row_mask:0xf bank_mask:0xf bound_ctrl:1
	v_pk_fma_f32 v[6:7], v[40:41], v[12:13], v[48:49] op_sel_hi:[1,0,1] neg_lo:[1,0,0] neg_hi:[1,0,0]
	v_pk_fma_f32 v[8:9], v[42:43], v[12:13], v[50:51] op_sel_hi:[1,0,1] neg_lo:[1,0,0] neg_hi:[1,0,0]
	s_waitcnt lgkmcnt(1)
	ds_read_b128 v[20:23], v10 offset:41216
	ds_read_b128 v[28:31], v10 offset:41728
	ds_read_b128 v[24:27], v10 offset:41472
	v_fma_mix_f32 v12, v6, v88, v180 op_sel_hi:[0,1,0]
	v_fma_mix_f32 v12, v7, v88, v12 op_sel:[0,1,0] op_sel_hi:[0,1,0]
	v_fma_mix_f32 v12, v8, v89, v12 op_sel_hi:[0,1,0]
	v_fma_mix_f32 v12, v9, v89, v12 op_sel:[0,1,0] op_sel_hi:[0,1,0]
	v_fma_mix_f32 v57, v6, v38, v180 op_sel_hi:[0,1,0]
	v_fma_mix_f32 v57, v7, v38, v57 op_sel:[0,1,0] op_sel_hi:[0,1,0]
	v_add_f32_dpp v12, v12, v12 row_ror:1 row_mask:0xf bank_mask:0xf bound_ctrl:1
	v_fma_mix_f32 v57, v8, v39, v57 op_sel_hi:[0,1,0]
	v_fma_mix_f32 v57, v9, v39, v57 op_sel:[0,1,0] op_sel_hi:[0,1,0]
	v_add_f32_dpp v12, v12, v12 row_ror:2 row_mask:0xf bank_mask:0xf bound_ctrl:1
	v_pk_fma_f32 v[48:49], v[96:97], v[72:73], v[6:7] op_sel_hi:[1,0,1]
	v_pk_fma_f32 v[50:51], v[98:99], v[72:73], v[8:9] op_sel_hi:[1,0,1]
	v_add_f32_dpp v12, v12, v12 row_ror:4 row_mask:0xf bank_mask:0xf bound_ctrl:1
	v_add_f32_dpp v137, v137, v137 row_ror:8 row_mask:0xf bank_mask:0xc
	v_add_f32_dpp v137, v129, v129 row_ror:8 row_mask:0xf bank_mask:0x3
	v_add_f32_dpp v12, v12, v12 row_ror:8 row_mask:0xf bank_mask:0xf bound_ctrl:1
	v_pk_fma_f32 v[6:7], v[92:93], v[12:13], v[48:49] op_sel_hi:[1,0,1] neg_lo:[1,0,0] neg_hi:[1,0,0]
	v_pk_fma_f32 v[8:9], v[94:95], v[12:13], v[50:51] op_sel_hi:[1,0,1] neg_lo:[1,0,0] neg_hi:[1,0,0]
	ds_read_b128 v[36:39], v10 offset:42240
	ds_read_b128 v[44:47], v10 offset:42752
	ds_read_b128 v[40:43], v10 offset:42496
	v_fma_mix_f32 v12, v6, v110, v180 op_sel_hi:[0,1,0]
	v_fma_mix_f32 v12, v7, v110, v12 op_sel:[0,1,0] op_sel_hi:[0,1,0]
	v_fma_mix_f32 v12, v8, v111, v12 op_sel_hi:[0,1,0]
	v_fma_mix_f32 v12, v9, v111, v12 op_sel:[0,1,0] op_sel_hi:[0,1,0]
	v_fma_mix_f32 v81, v6, v90, v180 op_sel_hi:[0,1,0]
	v_fma_mix_f32 v81, v7, v90, v81 op_sel:[0,1,0] op_sel_hi:[0,1,0]
	v_add_f32_dpp v12, v12, v12 row_ror:1 row_mask:0xf bank_mask:0xf bound_ctrl:1
	v_fma_mix_f32 v81, v8, v91, v81 op_sel_hi:[0,1,0]
	v_fma_mix_f32 v81, v9, v91, v81 op_sel:[0,1,0] op_sel_hi:[0,1,0]
	v_add_f32_dpp v12, v12, v12 row_ror:2 row_mask:0xf bank_mask:0xf bound_ctrl:1
	v_pk_fma_f32 v[48:49], v[118:119], v[72:73], v[6:7] op_sel:[0,1,0]
	v_pk_fma_f32 v[50:51], v[120:121], v[72:73], v[8:9] op_sel:[0,1,0]
	v_add_f32_dpp v12, v12, v12 row_ror:4 row_mask:0xf bank_mask:0xf bound_ctrl:1
	v_add_f32_dpp v134, v134, v134 row_ror:4 row_mask:0xf bank_mask:0xa
	v_add_f32_dpp v134, v130, v130 row_ror:12 row_mask:0xf bank_mask:0x5
	v_add_f32_dpp v135, v135, v135 row_ror:4 row_mask:0xf bank_mask:0xa
	v_add_f32_dpp v12, v12, v12 row_ror:8 row_mask:0xf bank_mask:0xf bound_ctrl:1
	v_pk_fma_f32 v[6:7], v[114:115], v[12:13], v[48:49] op_sel_hi:[1,0,1] neg_lo:[1,0,0] neg_hi:[1,0,0]
	v_pk_fma_f32 v[8:9], v[116:117], v[12:13], v[50:51] op_sel_hi:[1,0,1] neg_lo:[1,0,0] neg_hi:[1,0,0]
	v_pk_mul_f32 v[6:7], v[6:7], v[106:107]
	v_pk_mul_f32 v[8:9], v[8:9], v[108:109]
	s_waitcnt lgkmcnt(0)
	ds_read_b128 v[88:91], v10 offset:43264
	ds_read_b128 v[96:99], v10 offset:43776
	ds_read_b128 v[92:95], v10 offset:43520
	v_fma_mix_f32 v12, v6, v20, v180 op_sel_hi:[0,1,0]
	v_fma_mix_f32 v12, v7, v20, v12 op_sel:[0,1,0] op_sel_hi:[0,1,0]
	v_fma_mix_f32 v12, v8, v21, v12 op_sel_hi:[0,1,0]
	v_fma_mix_f32 v12, v9, v21, v12 op_sel:[0,1,0] op_sel_hi:[0,1,0]
	v_fma_mix_f32 v82, v6, v112, v180 op_sel_hi:[0,1,0]
	v_fma_mix_f32 v82, v7, v112, v82 op_sel:[0,1,0] op_sel_hi:[0,1,0]
	v_add_f32_dpp v12, v12, v12 row_ror:1 row_mask:0xf bank_mask:0xf bound_ctrl:1
	v_fma_mix_f32 v82, v8, v113, v82 op_sel_hi:[0,1,0]
	v_fma_mix_f32 v82, v9, v113, v82 op_sel:[0,1,0] op_sel_hi:[0,1,0]
	v_add_f32_dpp v12, v12, v12 row_ror:2 row_mask:0xf bank_mask:0xf bound_ctrl:1
	v_pk_fma_f32 v[48:49], v[28:29], v[66:67], v[6:7] op_sel_hi:[1,0,1]
	v_pk_fma_f32 v[50:51], v[30:31], v[66:67], v[8:9] op_sel_hi:[1,0,1]
	v_add_f32_dpp v12, v12, v12 row_ror:4 row_mask:0xf bank_mask:0xf bound_ctrl:1
	v_add_f32_dpp v135, v131, v131 row_ror:12 row_mask:0xf bank_mask:0x5
	v_add_f32_dpp v136, v136, v136 row_ror:4 row_mask:0xf bank_mask:0xa
	v_add_f32_dpp v136, v132, v132 row_ror:12 row_mask:0xf bank_mask:0x5
	v_add_f32_dpp v12, v12, v12 row_ror:8 row_mask:0xf bank_mask:0xf bound_ctrl:1
	v_pk_fma_f32 v[6:7], v[24:25], v[12:13], v[48:49] op_sel_hi:[1,0,1] neg_lo:[1,0,0] neg_hi:[1,0,0]
	v_pk_fma_f32 v[8:9], v[26:27], v[12:13], v[50:51] op_sel_hi:[1,0,1] neg_lo:[1,0,0] neg_hi:[1,0,0]
	ds_read_b128 v[110:113], v10 offset:44288
	ds_read_b128 v[106:109], v10 offset:44032
	ds_read_b128 v[118:121], v10 offset:44800
	ds_read_b128 v[114:117], v10 offset:44544
	ds_read_b128 v[70:73], v11 offset:2816
	v_fma_mix_f32 v12, v6, v36, v180 op_sel_hi:[0,1,0]
	v_fma_mix_f32 v12, v7, v36, v12 op_sel:[0,1,0] op_sel_hi:[0,1,0]
	v_fma_mix_f32 v12, v8, v37, v12 op_sel_hi:[0,1,0]
	v_fma_mix_f32 v12, v9, v37, v12 op_sel:[0,1,0] op_sel_hi:[0,1,0]
	v_fma_mix_f32 v83, v6, v22, v180 op_sel_hi:[0,1,0]
	v_fma_mix_f32 v83, v7, v22, v83 op_sel:[0,1,0] op_sel_hi:[0,1,0]
	v_add_f32_dpp v12, v12, v12 row_ror:1 row_mask:0xf bank_mask:0xf bound_ctrl:1
	v_fma_mix_f32 v83, v8, v23, v83 op_sel_hi:[0,1,0]
	v_fma_mix_f32 v83, v9, v23, v83 op_sel:[0,1,0] op_sel_hi:[0,1,0]
	v_add_f32_dpp v12, v12, v12 row_ror:2 row_mask:0xf bank_mask:0xf bound_ctrl:1
	v_pk_fma_f32 v[48:49], v[44:45], v[66:67], v[6:7] op_sel:[0,1,0]
	v_pk_fma_f32 v[50:51], v[46:47], v[66:67], v[8:9] op_sel:[0,1,0]
	v_add_f32_dpp v12, v12, v12 row_ror:4 row_mask:0xf bank_mask:0xf bound_ctrl:1
	v_add_f32_dpp v137, v137, v137 row_ror:4 row_mask:0xf bank_mask:0xa
	v_add_f32_dpp v137, v133, v133 row_ror:12 row_mask:0xf bank_mask:0x5
	v_add_f32_dpp v12, v12, v12 row_ror:8 row_mask:0xf bank_mask:0xf bound_ctrl:1
	v_pk_fma_f32 v[6:7], v[40:41], v[12:13], v[48:49] op_sel_hi:[1,0,1] neg_lo:[1,0,0] neg_hi:[1,0,0]
	v_pk_fma_f32 v[8:9], v[42:43], v[12:13], v[50:51] op_sel_hi:[1,0,1] neg_lo:[1,0,0] neg_hi:[1,0,0]
	s_waitcnt lgkmcnt(1)
	ds_read_b128 v[20:23], v10 offset:45312
	ds_read_b128 v[28:31], v10 offset:45824
	ds_read_b128 v[24:27], v10 offset:45568
	v_fma_mix_f32 v12, v6, v88, v180 op_sel_hi:[0,1,0]
	v_fma_mix_f32 v12, v7, v88, v12 op_sel:[0,1,0] op_sel_hi:[0,1,0]
	v_fma_mix_f32 v12, v8, v89, v12 op_sel_hi:[0,1,0]
	v_fma_mix_f32 v12, v9, v89, v12 op_sel:[0,1,0] op_sel_hi:[0,1,0]
	v_fma_mix_f32 v100, v6, v38, v180 op_sel_hi:[0,1,0]
	v_fma_mix_f32 v100, v7, v38, v100 op_sel:[0,1,0] op_sel_hi:[0,1,0]
	v_add_f32_dpp v12, v12, v12 row_ror:1 row_mask:0xf bank_mask:0xf bound_ctrl:1
	v_fma_mix_f32 v100, v8, v39, v100 op_sel_hi:[0,1,0]
	v_fma_mix_f32 v100, v9, v39, v100 op_sel:[0,1,0] op_sel_hi:[0,1,0]
	v_add_f32_dpp v12, v12, v12 row_ror:2 row_mask:0xf bank_mask:0xf bound_ctrl:1
	v_pk_fma_f32 v[48:49], v[96:97], v[68:69], v[6:7] op_sel_hi:[1,0,1]
	v_pk_fma_f32 v[50:51], v[98:99], v[68:69], v[8:9] op_sel_hi:[1,0,1]
	v_add_f32_dpp v12, v12, v12 row_ror:4 row_mask:0xf bank_mask:0xf bound_ctrl:1
	v_cndmask_b32_e64 v62, v136, v134, s[38:39]
	v_cndmask_b32_e64 v63, v134, v136, s[38:39]
	v_add_f32_dpp v12, v12, v12 row_ror:8 row_mask:0xf bank_mask:0xf bound_ctrl:1
	v_pk_fma_f32 v[6:7], v[92:93], v[12:13], v[48:49] op_sel_hi:[1,0,1] neg_lo:[1,0,0] neg_hi:[1,0,0]
	v_pk_fma_f32 v[8:9], v[94:95], v[12:13], v[50:51] op_sel_hi:[1,0,1] neg_lo:[1,0,0] neg_hi:[1,0,0]
	ds_read_b128 v[36:39], v10 offset:46336
	ds_read_b128 v[44:47], v10 offset:46848
	ds_read_b128 v[40:43], v10 offset:46592
	v_fma_mix_f32 v12, v6, v110, v180 op_sel_hi:[0,1,0]
	v_fma_mix_f32 v12, v7, v110, v12 op_sel:[0,1,0] op_sel_hi:[0,1,0]
	v_fma_mix_f32 v12, v8, v111, v12 op_sel_hi:[0,1,0]
	v_fma_mix_f32 v12, v9, v111, v12 op_sel:[0,1,0] op_sel_hi:[0,1,0]
	v_fma_mix_f32 v101, v6, v90, v180 op_sel_hi:[0,1,0]
	v_fma_mix_f32 v101, v7, v90, v101 op_sel:[0,1,0] op_sel_hi:[0,1,0]
	v_add_f32_dpp v12, v12, v12 row_ror:1 row_mask:0xf bank_mask:0xf bound_ctrl:1
	v_fma_mix_f32 v101, v8, v91, v101 op_sel_hi:[0,1,0]
	v_fma_mix_f32 v101, v9, v91, v101 op_sel:[0,1,0] op_sel_hi:[0,1,0]
	v_add_f32_dpp v12, v12, v12 row_ror:2 row_mask:0xf bank_mask:0xf bound_ctrl:1
	v_pk_fma_f32 v[48:49], v[118:119], v[68:69], v[6:7] op_sel:[0,1,0]
	v_pk_fma_f32 v[50:51], v[120:121], v[68:69], v[8:9] op_sel:[0,1,0]
	v_add_f32_dpp v12, v12, v12 row_ror:4 row_mask:0xf bank_mask:0xf bound_ctrl:1
	v_cndmask_b32_e64 v64, v137, v135, s[38:39]
	v_cndmask_b32_e64 v65, v135, v137, s[38:39]
	v_add_f32_dpp v12, v12, v12 row_ror:8 row_mask:0xf bank_mask:0xf bound_ctrl:1
	v_pk_fma_f32 v[6:7], v[114:115], v[12:13], v[48:49] op_sel_hi:[1,0,1] neg_lo:[1,0,0] neg_hi:[1,0,0]
	v_pk_fma_f32 v[8:9], v[116:117], v[12:13], v[50:51] op_sel_hi:[1,0,1] neg_lo:[1,0,0] neg_hi:[1,0,0]
	v_pk_mul_f32 v[6:7], v[6:7], v[106:107]
	v_pk_mul_f32 v[8:9], v[8:9], v[108:109]
	s_waitcnt lgkmcnt(0)
	ds_read_b128 v[88:91], v10 offset:47360
	ds_read_b128 v[96:99], v10 offset:47872
	ds_read_b128 v[92:95], v10 offset:47616
	v_fma_mix_f32 v12, v6, v20, v180 op_sel_hi:[0,1,0]
	v_fma_mix_f32 v12, v7, v20, v12 op_sel:[0,1,0] op_sel_hi:[0,1,0]
	v_fma_mix_f32 v12, v8, v21, v12 op_sel_hi:[0,1,0]
	v_fma_mix_f32 v12, v9, v21, v12 op_sel:[0,1,0] op_sel_hi:[0,1,0]
	v_fma_mix_f32 v102, v6, v112, v180 op_sel_hi:[0,1,0]
	v_fma_mix_f32 v102, v7, v112, v102 op_sel:[0,1,0] op_sel_hi:[0,1,0]
	v_add_f32_dpp v12, v12, v12 row_ror:1 row_mask:0xf bank_mask:0xf bound_ctrl:1
	v_fma_mix_f32 v102, v8, v113, v102 op_sel_hi:[0,1,0]
	v_fma_mix_f32 v102, v9, v113, v102 op_sel:[0,1,0] op_sel_hi:[0,1,0]
	v_add_f32_dpp v12, v12, v12 row_ror:2 row_mask:0xf bank_mask:0xf bound_ctrl:1
	v_pk_fma_f32 v[48:49], v[28:29], v[70:71], v[6:7] op_sel_hi:[1,0,1]
	v_pk_fma_f32 v[50:51], v[30:31], v[70:71], v[8:9] op_sel_hi:[1,0,1]
	v_add_f32_dpp v12, v12, v12 row_ror:4 row_mask:0xf bank_mask:0xf bound_ctrl:1
	v_add_f32_dpp v62, v63, v62 quad_perm:[2,3,0,1] row_mask:0xf bank_mask:0xf bound_ctrl:1
	v_add_f32_dpp v63, v65, v64 quad_perm:[2,3,0,1] row_mask:0xf bank_mask:0xf bound_ctrl:1
	v_add_f32_dpp v12, v12, v12 row_ror:8 row_mask:0xf bank_mask:0xf bound_ctrl:1
	v_pk_fma_f32 v[6:7], v[24:25], v[12:13], v[48:49] op_sel_hi:[1,0,1] neg_lo:[1,0,0] neg_hi:[1,0,0]
	v_pk_fma_f32 v[8:9], v[26:27], v[12:13], v[50:51] op_sel_hi:[1,0,1] neg_lo:[1,0,0] neg_hi:[1,0,0]
	ds_read_b128 v[110:113], v10 offset:48384
	ds_read_b128 v[106:109], v10 offset:48128
	ds_read_b128 v[118:121], v10 offset:48896
	ds_read_b128 v[114:117], v10 offset:48640
	ds_read_b128 v[66:69], v11 offset:3072
	v_fma_mix_f32 v12, v6, v36, v180 op_sel_hi:[0,1,0]
	v_fma_mix_f32 v12, v7, v36, v12 op_sel:[0,1,0] op_sel_hi:[0,1,0]
	v_fma_mix_f32 v12, v8, v37, v12 op_sel_hi:[0,1,0]
	v_fma_mix_f32 v12, v9, v37, v12 op_sel:[0,1,0] op_sel_hi:[0,1,0]
	v_fma_mix_f32 v103, v6, v22, v180 op_sel_hi:[0,1,0]
	v_fma_mix_f32 v103, v7, v22, v103 op_sel:[0,1,0] op_sel_hi:[0,1,0]
	v_add_f32_dpp v12, v12, v12 row_ror:1 row_mask:0xf bank_mask:0xf bound_ctrl:1
	v_fma_mix_f32 v103, v8, v23, v103 op_sel_hi:[0,1,0]
	v_fma_mix_f32 v103, v9, v23, v103 op_sel:[0,1,0] op_sel_hi:[0,1,0]
	v_add_f32_dpp v12, v12, v12 row_ror:2 row_mask:0xf bank_mask:0xf bound_ctrl:1
	v_pk_fma_f32 v[48:49], v[44:45], v[70:71], v[6:7] op_sel:[0,1,0]
	v_pk_fma_f32 v[50:51], v[46:47], v[70:71], v[8:9] op_sel:[0,1,0]
	v_add_f32_dpp v12, v12, v12 row_ror:4 row_mask:0xf bank_mask:0xf bound_ctrl:1
	v_cndmask_b32_e64 v65, v63, v62, s[40:41]
	v_cndmask_b32_e64 v62, v62, v63, s[40:41]
	v_add_f32_dpp v12, v12, v12 row_ror:8 row_mask:0xf bank_mask:0xf bound_ctrl:1
	v_pk_fma_f32 v[6:7], v[40:41], v[12:13], v[48:49] op_sel_hi:[1,0,1] neg_lo:[1,0,0] neg_hi:[1,0,0]
	v_pk_fma_f32 v[8:9], v[42:43], v[12:13], v[50:51] op_sel_hi:[1,0,1] neg_lo:[1,0,0] neg_hi:[1,0,0]
	s_waitcnt lgkmcnt(1)
	ds_read_b128 v[20:23], v10 offset:49408
	ds_read_b128 v[28:31], v10 offset:49920
	ds_read_b128 v[24:27], v10 offset:49664
	v_fma_mix_f32 v12, v6, v88, v180 op_sel_hi:[0,1,0]
	v_fma_mix_f32 v12, v7, v88, v12 op_sel:[0,1,0] op_sel_hi:[0,1,0]
	v_fma_mix_f32 v12, v8, v89, v12 op_sel_hi:[0,1,0]
	v_fma_mix_f32 v12, v9, v89, v12 op_sel:[0,1,0] op_sel_hi:[0,1,0]
	v_fma_mix_f32 v104, v6, v38, v180 op_sel_hi:[0,1,0]
	v_fma_mix_f32 v104, v7, v38, v104 op_sel:[0,1,0] op_sel_hi:[0,1,0]
	v_add_f32_dpp v12, v12, v12 row_ror:1 row_mask:0xf bank_mask:0xf bound_ctrl:1
	v_fma_mix_f32 v104, v8, v39, v104 op_sel_hi:[0,1,0]
	v_fma_mix_f32 v104, v9, v39, v104 op_sel:[0,1,0] op_sel_hi:[0,1,0]
	v_add_f32_dpp v12, v12, v12 row_ror:2 row_mask:0xf bank_mask:0xf bound_ctrl:1
	v_pk_fma_f32 v[48:49], v[96:97], v[72:73], v[6:7] op_sel_hi:[1,0,1]
	v_pk_fma_f32 v[50:51], v[98:99], v[72:73], v[8:9] op_sel_hi:[1,0,1]
	v_add_f32_dpp v12, v12, v12 row_ror:4 row_mask:0xf bank_mask:0xf bound_ctrl:1
	v_add_f32_dpp v62, v62, v65 quad_perm:[1,0,3,2] row_mask:0xf bank_mask:0xf bound_ctrl:1
	v_cvt_pk_bf16_f32 v62, v62, v62
	v_add_f32_dpp v12, v12, v12 row_ror:8 row_mask:0xf bank_mask:0xf bound_ctrl:1
	v_pk_fma_f32 v[6:7], v[92:93], v[12:13], v[48:49] op_sel_hi:[1,0,1] neg_lo:[1,0,0] neg_hi:[1,0,0]
	v_pk_fma_f32 v[8:9], v[94:95], v[12:13], v[50:51] op_sel_hi:[1,0,1] neg_lo:[1,0,0] neg_hi:[1,0,0]
	ds_read_b128 v[36:39], v10 offset:50432
	ds_read_b128 v[44:47], v10 offset:50944
	ds_read_b128 v[40:43], v10 offset:50688
	v_fma_mix_f32 v12, v6, v110, v180 op_sel_hi:[0,1,0]
	v_fma_mix_f32 v12, v7, v110, v12 op_sel:[0,1,0] op_sel_hi:[0,1,0]
	v_fma_mix_f32 v12, v8, v111, v12 op_sel_hi:[0,1,0]
	v_fma_mix_f32 v12, v9, v111, v12 op_sel:[0,1,0] op_sel_hi:[0,1,0]
	v_fma_mix_f32 v105, v6, v90, v180 op_sel_hi:[0,1,0]
	v_fma_mix_f32 v105, v7, v90, v105 op_sel:[0,1,0] op_sel_hi:[0,1,0]
	v_add_f32_dpp v12, v12, v12 row_ror:1 row_mask:0xf bank_mask:0xf bound_ctrl:1
	v_fma_mix_f32 v105, v8, v91, v105 op_sel_hi:[0,1,0]
	v_fma_mix_f32 v105, v9, v91, v105 op_sel:[0,1,0] op_sel_hi:[0,1,0]
	v_add_f32_dpp v12, v12, v12 row_ror:2 row_mask:0xf bank_mask:0xf bound_ctrl:1
	v_pk_fma_f32 v[48:49], v[118:119], v[72:73], v[6:7] op_sel:[0,1,0]
	v_pk_fma_f32 v[50:51], v[120:121], v[72:73], v[8:9] op_sel:[0,1,0]
	v_add_f32_dpp v12, v12, v12 row_ror:4 row_mask:0xf bank_mask:0xf bound_ctrl:1
	global_store_short v[2:3], v62, off
	v_lshl_add_u64 v[2:3], v[2:3], 0, s[84:85]
	v_add_f32_dpp v12, v12, v12 row_ror:8 row_mask:0xf bank_mask:0xf bound_ctrl:1
	v_pk_fma_f32 v[6:7], v[114:115], v[12:13], v[48:49] op_sel_hi:[1,0,1] neg_lo:[1,0,0] neg_hi:[1,0,0]
	v_pk_fma_f32 v[8:9], v[116:117], v[12:13], v[50:51] op_sel_hi:[1,0,1] neg_lo:[1,0,0] neg_hi:[1,0,0]
	v_pk_mul_f32 v[6:7], v[6:7], v[106:107]
	v_pk_mul_f32 v[8:9], v[8:9], v[108:109]
	s_waitcnt lgkmcnt(0)
	ds_read_b128 v[88:91], v10 offset:51456
	ds_read_b128 v[96:99], v10 offset:51968
	ds_read_b128 v[92:95], v10 offset:51712
	v_fma_mix_f32 v12, v6, v20, v180 op_sel_hi:[0,1,0]
	v_fma_mix_f32 v12, v7, v20, v12 op_sel:[0,1,0] op_sel_hi:[0,1,0]
	v_fma_mix_f32 v12, v8, v21, v12 op_sel_hi:[0,1,0]
	v_fma_mix_f32 v12, v9, v21, v12 op_sel:[0,1,0] op_sel_hi:[0,1,0]
	v_fma_mix_f32 v61, v6, v112, v180 op_sel_hi:[0,1,0]
	v_fma_mix_f32 v61, v7, v112, v61 op_sel:[0,1,0] op_sel_hi:[0,1,0]
	v_add_f32_dpp v12, v12, v12 row_ror:1 row_mask:0xf bank_mask:0xf bound_ctrl:1
	v_fma_mix_f32 v61, v8, v113, v61 op_sel_hi:[0,1,0]
	v_fma_mix_f32 v61, v9, v113, v61 op_sel:[0,1,0] op_sel_hi:[0,1,0]
	v_add_f32_dpp v12, v12, v12 row_ror:2 row_mask:0xf bank_mask:0xf bound_ctrl:1
	v_pk_fma_f32 v[48:49], v[28:29], v[66:67], v[6:7] op_sel_hi:[1,0,1]
	v_pk_fma_f32 v[50:51], v[30:31], v[66:67], v[8:9] op_sel_hi:[1,0,1]
	v_add_f32_dpp v12, v12, v12 row_ror:4 row_mask:0xf bank_mask:0xf bound_ctrl:1
	s_nop 1
	v_add_f32_dpp v12, v12, v12 row_ror:8 row_mask:0xf bank_mask:0xf bound_ctrl:1
	v_pk_fma_f32 v[6:7], v[24:25], v[12:13], v[48:49] op_sel_hi:[1,0,1] neg_lo:[1,0,0] neg_hi:[1,0,0]
	v_pk_fma_f32 v[8:9], v[26:27], v[12:13], v[50:51] op_sel_hi:[1,0,1] neg_lo:[1,0,0] neg_hi:[1,0,0]
	ds_read_b128 v[110:113], v10 offset:52480
	ds_read_b128 v[106:109], v10 offset:52224
	ds_read_b128 v[118:121], v10 offset:52992
	ds_read_b128 v[114:117], v10 offset:52736
	ds_read_b128 v[70:73], v11 offset:3328
	v_fma_mix_f32 v12, v6, v36, v180 op_sel_hi:[0,1,0]
	v_fma_mix_f32 v12, v7, v36, v12 op_sel:[0,1,0] op_sel_hi:[0,1,0]
	v_fma_mix_f32 v12, v8, v37, v12 op_sel_hi:[0,1,0]
	v_fma_mix_f32 v12, v9, v37, v12 op_sel:[0,1,0] op_sel_hi:[0,1,0]
	v_fma_mix_f32 v122, v6, v22, v180 op_sel_hi:[0,1,0]
	v_fma_mix_f32 v122, v7, v22, v122 op_sel:[0,1,0] op_sel_hi:[0,1,0]
	v_add_f32_dpp v12, v12, v12 row_ror:1 row_mask:0xf bank_mask:0xf bound_ctrl:1
	v_fma_mix_f32 v122, v8, v23, v122 op_sel_hi:[0,1,0]
	v_fma_mix_f32 v122, v9, v23, v122 op_sel:[0,1,0] op_sel_hi:[0,1,0]
	v_add_f32_dpp v12, v12, v12 row_ror:2 row_mask:0xf bank_mask:0xf bound_ctrl:1
	v_pk_fma_f32 v[48:49], v[44:45], v[66:67], v[6:7] op_sel:[0,1,0]
	v_pk_fma_f32 v[50:51], v[46:47], v[66:67], v[8:9] op_sel:[0,1,0]
	v_add_f32_dpp v12, v12, v12 row_ror:4 row_mask:0xf bank_mask:0xf bound_ctrl:1
	v_add_f32_dpp v83, v83, v83 row_ror:8 row_mask:0xf bank_mask:0xc
	v_add_f32_dpp v83, v52, v52 row_ror:8 row_mask:0xf bank_mask:0x3
	v_add_f32_dpp v100, v100, v100 row_ror:8 row_mask:0xf bank_mask:0xc
	v_add_f32_dpp v12, v12, v12 row_ror:8 row_mask:0xf bank_mask:0xf bound_ctrl:1
	v_pk_fma_f32 v[6:7], v[40:41], v[12:13], v[48:49] op_sel_hi:[1,0,1] neg_lo:[1,0,0] neg_hi:[1,0,0]
	v_pk_fma_f32 v[8:9], v[42:43], v[12:13], v[50:51] op_sel_hi:[1,0,1] neg_lo:[1,0,0] neg_hi:[1,0,0]
	s_waitcnt lgkmcnt(1)
	ds_read_b128 v[20:23], v10 offset:53504
	ds_read_b128 v[28:31], v10 offset:54016
	ds_read_b128 v[24:27], v10 offset:53760
	v_fma_mix_f32 v12, v6, v88, v180 op_sel_hi:[0,1,0]
	v_fma_mix_f32 v12, v7, v88, v12 op_sel:[0,1,0] op_sel_hi:[0,1,0]
	v_fma_mix_f32 v12, v8, v89, v12 op_sel_hi:[0,1,0]
	v_fma_mix_f32 v12, v9, v89, v12 op_sel:[0,1,0] op_sel_hi:[0,1,0]
	v_fma_mix_f32 v123, v6, v38, v180 op_sel_hi:[0,1,0]
	v_fma_mix_f32 v123, v7, v38, v123 op_sel:[0,1,0] op_sel_hi:[0,1,0]
	v_add_f32_dpp v12, v12, v12 row_ror:1 row_mask:0xf bank_mask:0xf bound_ctrl:1
	v_fma_mix_f32 v123, v8, v39, v123 op_sel_hi:[0,1,0]
	v_fma_mix_f32 v123, v9, v39, v123 op_sel:[0,1,0] op_sel_hi:[0,1,0]
	v_add_f32_dpp v12, v12, v12 row_ror:2 row_mask:0xf bank_mask:0xf bound_ctrl:1
	v_pk_fma_f32 v[48:49], v[96:97], v[68:69], v[6:7] op_sel_hi:[1,0,1]
	v_pk_fma_f32 v[50:51], v[98:99], v[68:69], v[8:9] op_sel_hi:[1,0,1]
	v_add_f32_dpp v12, v12, v12 row_ror:4 row_mask:0xf bank_mask:0xf bound_ctrl:1
	v_add_f32_dpp v100, v53, v53 row_ror:8 row_mask:0xf bank_mask:0x3
	v_add_f32_dpp v101, v101, v101 row_ror:8 row_mask:0xf bank_mask:0xc
	v_add_f32_dpp v101, v54, v54 row_ror:8 row_mask:0xf bank_mask:0x3
	v_add_f32_dpp v12, v12, v12 row_ror:8 row_mask:0xf bank_mask:0xf bound_ctrl:1
	v_pk_fma_f32 v[6:7], v[92:93], v[12:13], v[48:49] op_sel_hi:[1,0,1] neg_lo:[1,0,0] neg_hi:[1,0,0]
	v_pk_fma_f32 v[8:9], v[94:95], v[12:13], v[50:51] op_sel_hi:[1,0,1] neg_lo:[1,0,0] neg_hi:[1,0,0]
	ds_read_b128 v[36:39], v10 offset:54528
	ds_read_b128 v[44:47], v10 offset:55040
	ds_read_b128 v[40:43], v10 offset:54784
	v_fma_mix_f32 v12, v6, v110, v180 op_sel_hi:[0,1,0]
	v_fma_mix_f32 v12, v7, v110, v12 op_sel:[0,1,0] op_sel_hi:[0,1,0]
	v_fma_mix_f32 v12, v8, v111, v12 op_sel_hi:[0,1,0]
	v_fma_mix_f32 v12, v9, v111, v12 op_sel:[0,1,0] op_sel_hi:[0,1,0]
	v_fma_mix_f32 v124, v6, v90, v180 op_sel_hi:[0,1,0]
	v_fma_mix_f32 v124, v7, v90, v124 op_sel:[0,1,0] op_sel_hi:[0,1,0]
	v_add_f32_dpp v12, v12, v12 row_ror:1 row_mask:0xf bank_mask:0xf bound_ctrl:1
	v_fma_mix_f32 v124, v8, v91, v124 op_sel_hi:[0,1,0]
	v_fma_mix_f32 v124, v9, v91, v124 op_sel:[0,1,0] op_sel_hi:[0,1,0]
	v_add_f32_dpp v12, v12, v12 row_ror:2 row_mask:0xf bank_mask:0xf bound_ctrl:1
	v_pk_fma_f32 v[48:49], v[118:119], v[68:69], v[6:7] op_sel:[0,1,0]
	v_pk_fma_f32 v[50:51], v[120:121], v[68:69], v[8:9] op_sel:[0,1,0]
	v_add_f32_dpp v12, v12, v12 row_ror:4 row_mask:0xf bank_mask:0xf bound_ctrl:1
	v_add_f32_dpp v102, v102, v102 row_ror:8 row_mask:0xf bank_mask:0xc
	v_add_f32_dpp v102, v55, v55 row_ror:8 row_mask:0xf bank_mask:0x3
	v_add_f32_dpp v103, v103, v103 row_ror:8 row_mask:0xf bank_mask:0xc
	v_add_f32_dpp v12, v12, v12 row_ror:8 row_mask:0xf bank_mask:0xf bound_ctrl:1
	v_pk_fma_f32 v[6:7], v[114:115], v[12:13], v[48:49] op_sel_hi:[1,0,1] neg_lo:[1,0,0] neg_hi:[1,0,0]
	v_pk_fma_f32 v[8:9], v[116:117], v[12:13], v[50:51] op_sel_hi:[1,0,1] neg_lo:[1,0,0] neg_hi:[1,0,0]
	v_pk_mul_f32 v[6:7], v[6:7], v[106:107]
	v_pk_mul_f32 v[8:9], v[8:9], v[108:109]
	s_waitcnt lgkmcnt(0)
	ds_read_b128 v[88:91], v10 offset:55552
	ds_read_b128 v[96:99], v10 offset:56064
	ds_read_b128 v[92:95], v10 offset:55808
	v_fma_mix_f32 v12, v6, v20, v180 op_sel_hi:[0,1,0]
	v_fma_mix_f32 v12, v7, v20, v12 op_sel:[0,1,0] op_sel_hi:[0,1,0]
	v_fma_mix_f32 v12, v8, v21, v12 op_sel_hi:[0,1,0]
	v_fma_mix_f32 v12, v9, v21, v12 op_sel:[0,1,0] op_sel_hi:[0,1,0]
	v_fma_mix_f32 v125, v6, v112, v180 op_sel_hi:[0,1,0]
	v_fma_mix_f32 v125, v7, v112, v125 op_sel:[0,1,0] op_sel_hi:[0,1,0]
	v_add_f32_dpp v12, v12, v12 row_ror:1 row_mask:0xf bank_mask:0xf bound_ctrl:1
	v_fma_mix_f32 v125, v8, v113, v125 op_sel_hi:[0,1,0]
	v_fma_mix_f32 v125, v9, v113, v125 op_sel:[0,1,0] op_sel_hi:[0,1,0]
	v_add_f32_dpp v12, v12, v12 row_ror:2 row_mask:0xf bank_mask:0xf bound_ctrl:1
	v_pk_fma_f32 v[48:49], v[28:29], v[70:71], v[6:7] op_sel_hi:[1,0,1]
	v_pk_fma_f32 v[50:51], v[30:31], v[70:71], v[8:9] op_sel_hi:[1,0,1]
	v_add_f32_dpp v12, v12, v12 row_ror:4 row_mask:0xf bank_mask:0xf bound_ctrl:1
	v_add_f32_dpp v103, v56, v56 row_ror:8 row_mask:0xf bank_mask:0x3
	v_add_f32_dpp v104, v104, v104 row_ror:8 row_mask:0xf bank_mask:0xc
	v_add_f32_dpp v104, v57, v57 row_ror:8 row_mask:0xf bank_mask:0x3
	v_add_f32_dpp v12, v12, v12 row_ror:8 row_mask:0xf bank_mask:0xf bound_ctrl:1
	v_pk_fma_f32 v[6:7], v[24:25], v[12:13], v[48:49] op_sel_hi:[1,0,1] neg_lo:[1,0,0] neg_hi:[1,0,0]
	v_pk_fma_f32 v[8:9], v[26:27], v[12:13], v[50:51] op_sel_hi:[1,0,1] neg_lo:[1,0,0] neg_hi:[1,0,0]
	ds_read_b128 v[110:113], v10 offset:56576
	ds_read_b128 v[106:109], v10 offset:56320
	ds_read_b128 v[118:121], v10 offset:57088
	ds_read_b128 v[114:117], v10 offset:56832
	ds_read_b128 v[66:69], v11 offset:3584
	v_fma_mix_f32 v12, v6, v36, v180 op_sel_hi:[0,1,0]
	v_fma_mix_f32 v12, v7, v36, v12 op_sel:[0,1,0] op_sel_hi:[0,1,0]
	v_fma_mix_f32 v12, v8, v37, v12 op_sel_hi:[0,1,0]
	v_fma_mix_f32 v12, v9, v37, v12 op_sel:[0,1,0] op_sel_hi:[0,1,0]
	v_fma_mix_f32 v126, v6, v22, v180 op_sel_hi:[0,1,0]
	v_fma_mix_f32 v126, v7, v22, v126 op_sel:[0,1,0] op_sel_hi:[0,1,0]
	v_add_f32_dpp v12, v12, v12 row_ror:1 row_mask:0xf bank_mask:0xf bound_ctrl:1
	v_fma_mix_f32 v126, v8, v23, v126 op_sel_hi:[0,1,0]
	v_fma_mix_f32 v126, v9, v23, v126 op_sel:[0,1,0] op_sel_hi:[0,1,0]
	v_add_f32_dpp v12, v12, v12 row_ror:2 row_mask:0xf bank_mask:0xf bound_ctrl:1
	v_pk_fma_f32 v[48:49], v[44:45], v[70:71], v[6:7] op_sel:[0,1,0]
	v_pk_fma_f32 v[50:51], v[46:47], v[70:71], v[8:9] op_sel:[0,1,0]
	v_add_f32_dpp v12, v12, v12 row_ror:4 row_mask:0xf bank_mask:0xf bound_ctrl:1
	v_add_f32_dpp v105, v105, v105 row_ror:8 row_mask:0xf bank_mask:0xc
	v_add_f32_dpp v105, v81, v81 row_ror:8 row_mask:0xf bank_mask:0x3
	v_add_f32_dpp v12, v12, v12 row_ror:8 row_mask:0xf bank_mask:0xf bound_ctrl:1
	v_pk_fma_f32 v[6:7], v[40:41], v[12:13], v[48:49] op_sel_hi:[1,0,1] neg_lo:[1,0,0] neg_hi:[1,0,0]
	v_pk_fma_f32 v[8:9], v[42:43], v[12:13], v[50:51] op_sel_hi:[1,0,1] neg_lo:[1,0,0] neg_hi:[1,0,0]
	s_waitcnt lgkmcnt(1)
	ds_read_b128 v[20:23], v10 offset:57600
	ds_read_b128 v[28:31], v10 offset:58112
	ds_read_b128 v[24:27], v10 offset:57856
	v_fma_mix_f32 v12, v6, v88, v180 op_sel_hi:[0,1,0]
	v_fma_mix_f32 v12, v7, v88, v12 op_sel:[0,1,0] op_sel_hi:[0,1,0]
	v_fma_mix_f32 v12, v8, v89, v12 op_sel_hi:[0,1,0]
	v_fma_mix_f32 v12, v9, v89, v12 op_sel:[0,1,0] op_sel_hi:[0,1,0]
	v_fma_mix_f32 v127, v6, v38, v180 op_sel_hi:[0,1,0]
	v_fma_mix_f32 v127, v7, v38, v127 op_sel:[0,1,0] op_sel_hi:[0,1,0]
	v_add_f32_dpp v12, v12, v12 row_ror:1 row_mask:0xf bank_mask:0xf bound_ctrl:1
	v_fma_mix_f32 v127, v8, v39, v127 op_sel_hi:[0,1,0]
	v_fma_mix_f32 v127, v9, v39, v127 op_sel:[0,1,0] op_sel_hi:[0,1,0]
	v_add_f32_dpp v12, v12, v12 row_ror:2 row_mask:0xf bank_mask:0xf bound_ctrl:1
	v_pk_fma_f32 v[48:49], v[96:97], v[72:73], v[6:7] op_sel_hi:[1,0,1]
	v_pk_fma_f32 v[50:51], v[98:99], v[72:73], v[8:9] op_sel_hi:[1,0,1]
	v_add_f32_dpp v12, v12, v12 row_ror:4 row_mask:0xf bank_mask:0xf bound_ctrl:1
	v_add_f32_dpp v61, v61, v61 row_ror:8 row_mask:0xf bank_mask:0xc
	v_add_f32_dpp v61, v82, v82 row_ror:8 row_mask:0xf bank_mask:0x3
	v_add_f32_dpp v12, v12, v12 row_ror:8 row_mask:0xf bank_mask:0xf bound_ctrl:1
	v_pk_fma_f32 v[6:7], v[92:93], v[12:13], v[48:49] op_sel_hi:[1,0,1] neg_lo:[1,0,0] neg_hi:[1,0,0]
	v_pk_fma_f32 v[8:9], v[94:95], v[12:13], v[50:51] op_sel_hi:[1,0,1] neg_lo:[1,0,0] neg_hi:[1,0,0]
	ds_read_b128 v[36:39], v10 offset:58624
	ds_read_b128 v[44:47], v10 offset:59136
	ds_read_b128 v[40:43], v10 offset:58880
	v_fma_mix_f32 v12, v6, v110, v180 op_sel_hi:[0,1,0]
	v_fma_mix_f32 v12, v7, v110, v12 op_sel:[0,1,0] op_sel_hi:[0,1,0]
	v_fma_mix_f32 v12, v8, v111, v12 op_sel_hi:[0,1,0]
	v_fma_mix_f32 v12, v9, v111, v12 op_sel:[0,1,0] op_sel_hi:[0,1,0]
	v_fma_mix_f32 v128, v6, v90, v180 op_sel_hi:[0,1,0]
	v_fma_mix_f32 v128, v7, v90, v128 op_sel:[0,1,0] op_sel_hi:[0,1,0]
	v_add_f32_dpp v12, v12, v12 row_ror:1 row_mask:0xf bank_mask:0xf bound_ctrl:1
	v_fma_mix_f32 v128, v8, v91, v128 op_sel_hi:[0,1,0]
	v_fma_mix_f32 v128, v9, v91, v128 op_sel:[0,1,0] op_sel_hi:[0,1,0]
	v_add_f32_dpp v12, v12, v12 row_ror:2 row_mask:0xf bank_mask:0xf bound_ctrl:1
	v_pk_fma_f32 v[48:49], v[118:119], v[72:73], v[6:7] op_sel:[0,1,0]
	v_pk_fma_f32 v[50:51], v[120:121], v[72:73], v[8:9] op_sel:[0,1,0]
	v_add_f32_dpp v12, v12, v12 row_ror:4 row_mask:0xf bank_mask:0xf bound_ctrl:1
	v_add_f32_dpp v103, v103, v103 row_ror:4 row_mask:0xf bank_mask:0xa
	v_add_f32_dpp v103, v83, v83 row_ror:12 row_mask:0xf bank_mask:0x5
	v_add_f32_dpp v104, v104, v104 row_ror:4 row_mask:0xf bank_mask:0xa
	v_add_f32_dpp v12, v12, v12 row_ror:8 row_mask:0xf bank_mask:0xf bound_ctrl:1
	v_pk_fma_f32 v[6:7], v[114:115], v[12:13], v[48:49] op_sel_hi:[1,0,1] neg_lo:[1,0,0] neg_hi:[1,0,0]
	v_pk_fma_f32 v[8:9], v[116:117], v[12:13], v[50:51] op_sel_hi:[1,0,1] neg_lo:[1,0,0] neg_hi:[1,0,0]
	v_pk_mul_f32 v[6:7], v[6:7], v[106:107]
	v_pk_mul_f32 v[8:9], v[8:9], v[108:109]
	s_waitcnt lgkmcnt(0)
	ds_read_b128 v[88:91], v10 offset:59648
	ds_read_b128 v[96:99], v10 offset:60160
	ds_read_b128 v[92:95], v10 offset:59904
	v_fma_mix_f32 v12, v6, v20, v180 op_sel_hi:[0,1,0]
	v_fma_mix_f32 v12, v7, v20, v12 op_sel:[0,1,0] op_sel_hi:[0,1,0]
	v_fma_mix_f32 v12, v8, v21, v12 op_sel_hi:[0,1,0]
	v_fma_mix_f32 v12, v9, v21, v12 op_sel:[0,1,0] op_sel_hi:[0,1,0]
	v_fma_mix_f32 v129, v6, v112, v180 op_sel_hi:[0,1,0]
	v_fma_mix_f32 v129, v7, v112, v129 op_sel:[0,1,0] op_sel_hi:[0,1,0]
	v_add_f32_dpp v12, v12, v12 row_ror:1 row_mask:0xf bank_mask:0xf bound_ctrl:1
	v_fma_mix_f32 v129, v8, v113, v129 op_sel_hi:[0,1,0]
	v_fma_mix_f32 v129, v9, v113, v129 op_sel:[0,1,0] op_sel_hi:[0,1,0]
	v_add_f32_dpp v12, v12, v12 row_ror:2 row_mask:0xf bank_mask:0xf bound_ctrl:1
	v_pk_fma_f32 v[48:49], v[28:29], v[66:67], v[6:7] op_sel_hi:[1,0,1]
	v_pk_fma_f32 v[50:51], v[30:31], v[66:67], v[8:9] op_sel_hi:[1,0,1]
	v_add_f32_dpp v12, v12, v12 row_ror:4 row_mask:0xf bank_mask:0xf bound_ctrl:1
	v_add_f32_dpp v104, v100, v100 row_ror:12 row_mask:0xf bank_mask:0x5
	v_add_f32_dpp v105, v105, v105 row_ror:4 row_mask:0xf bank_mask:0xa
	v_add_f32_dpp v105, v101, v101 row_ror:12 row_mask:0xf bank_mask:0x5
	v_add_f32_dpp v12, v12, v12 row_ror:8 row_mask:0xf bank_mask:0xf bound_ctrl:1
	v_pk_fma_f32 v[6:7], v[24:25], v[12:13], v[48:49] op_sel_hi:[1,0,1] neg_lo:[1,0,0] neg_hi:[1,0,0]
	v_pk_fma_f32 v[8:9], v[26:27], v[12:13], v[50:51] op_sel_hi:[1,0,1] neg_lo:[1,0,0] neg_hi:[1,0,0]
	ds_read_b128 v[110:113], v10 offset:60672
	ds_read_b128 v[106:109], v10 offset:60416
	ds_read_b128 v[118:121], v10 offset:61184
	ds_read_b128 v[114:117], v10 offset:60928
	ds_read_b128 v[70:73], v11 offset:3840
	v_fma_mix_f32 v12, v6, v36, v180 op_sel_hi:[0,1,0]
	v_fma_mix_f32 v12, v7, v36, v12 op_sel:[0,1,0] op_sel_hi:[0,1,0]
	v_fma_mix_f32 v12, v8, v37, v12 op_sel_hi:[0,1,0]
	v_fma_mix_f32 v12, v9, v37, v12 op_sel:[0,1,0] op_sel_hi:[0,1,0]
	v_fma_mix_f32 v130, v6, v22, v180 op_sel_hi:[0,1,0]
	v_fma_mix_f32 v130, v7, v22, v130 op_sel:[0,1,0] op_sel_hi:[0,1,0]
	v_add_f32_dpp v12, v12, v12 row_ror:1 row_mask:0xf bank_mask:0xf bound_ctrl:1
	v_fma_mix_f32 v130, v8, v23, v130 op_sel_hi:[0,1,0]
	v_fma_mix_f32 v130, v9, v23, v130 op_sel:[0,1,0] op_sel_hi:[0,1,0]
	v_add_f32_dpp v12, v12, v12 row_ror:2 row_mask:0xf bank_mask:0xf bound_ctrl:1
	v_pk_fma_f32 v[48:49], v[44:45], v[66:67], v[6:7] op_sel:[0,1,0]
	v_pk_fma_f32 v[50:51], v[46:47], v[66:67], v[8:9] op_sel:[0,1,0]
	v_add_f32_dpp v12, v12, v12 row_ror:4 row_mask:0xf bank_mask:0xf bound_ctrl:1
	v_add_f32_dpp v61, v61, v61 row_ror:4 row_mask:0xf bank_mask:0xa
	v_add_f32_dpp v61, v102, v102 row_ror:12 row_mask:0xf bank_mask:0x5
	v_add_f32_dpp v12, v12, v12 row_ror:8 row_mask:0xf bank_mask:0xf bound_ctrl:1
	v_pk_fma_f32 v[6:7], v[40:41], v[12:13], v[48:49] op_sel_hi:[1,0,1] neg_lo:[1,0,0] neg_hi:[1,0,0]
	v_pk_fma_f32 v[8:9], v[42:43], v[12:13], v[50:51] op_sel_hi:[1,0,1] neg_lo:[1,0,0] neg_hi:[1,0,0]
	s_waitcnt lgkmcnt(1)
	ds_read_b128 v[20:23], v10 offset:61696
	ds_read_b128 v[28:31], v10 offset:62208
	ds_read_b128 v[24:27], v10 offset:61952
	v_fma_mix_f32 v12, v6, v88, v180 op_sel_hi:[0,1,0]
	v_fma_mix_f32 v12, v7, v88, v12 op_sel:[0,1,0] op_sel_hi:[0,1,0]
	v_fma_mix_f32 v12, v8, v89, v12 op_sel_hi:[0,1,0]
	v_fma_mix_f32 v12, v9, v89, v12 op_sel:[0,1,0] op_sel_hi:[0,1,0]
	v_fma_mix_f32 v131, v6, v38, v180 op_sel_hi:[0,1,0]
	v_fma_mix_f32 v131, v7, v38, v131 op_sel:[0,1,0] op_sel_hi:[0,1,0]
	v_add_f32_dpp v12, v12, v12 row_ror:1 row_mask:0xf bank_mask:0xf bound_ctrl:1
	v_fma_mix_f32 v131, v8, v39, v131 op_sel_hi:[0,1,0]
	v_fma_mix_f32 v131, v9, v39, v131 op_sel:[0,1,0] op_sel_hi:[0,1,0]
	v_add_f32_dpp v12, v12, v12 row_ror:2 row_mask:0xf bank_mask:0xf bound_ctrl:1
	v_pk_fma_f32 v[48:49], v[96:97], v[68:69], v[6:7] op_sel_hi:[1,0,1]
	v_pk_fma_f32 v[50:51], v[98:99], v[68:69], v[8:9] op_sel_hi:[1,0,1]
	v_add_f32_dpp v12, v12, v12 row_ror:4 row_mask:0xf bank_mask:0xf bound_ctrl:1
	v_cndmask_b32_e64 v62, v105, v103, s[38:39]
	v_cndmask_b32_e64 v63, v103, v105, s[38:39]
	v_add_f32_dpp v12, v12, v12 row_ror:8 row_mask:0xf bank_mask:0xf bound_ctrl:1
	v_pk_fma_f32 v[6:7], v[92:93], v[12:13], v[48:49] op_sel_hi:[1,0,1] neg_lo:[1,0,0] neg_hi:[1,0,0]
	v_pk_fma_f32 v[8:9], v[94:95], v[12:13], v[50:51] op_sel_hi:[1,0,1] neg_lo:[1,0,0] neg_hi:[1,0,0]
	ds_read_b128 v[36:39], v10 offset:62720
	ds_read_b128 v[44:47], v10 offset:63232
	ds_read_b128 v[40:43], v10 offset:62976
	v_fma_mix_f32 v12, v6, v110, v180 op_sel_hi:[0,1,0]
	v_fma_mix_f32 v12, v7, v110, v12 op_sel:[0,1,0] op_sel_hi:[0,1,0]
	v_fma_mix_f32 v12, v8, v111, v12 op_sel_hi:[0,1,0]
	v_fma_mix_f32 v12, v9, v111, v12 op_sel:[0,1,0] op_sel_hi:[0,1,0]
	v_fma_mix_f32 v132, v6, v90, v180 op_sel_hi:[0,1,0]
	v_fma_mix_f32 v132, v7, v90, v132 op_sel:[0,1,0] op_sel_hi:[0,1,0]
	v_add_f32_dpp v12, v12, v12 row_ror:1 row_mask:0xf bank_mask:0xf bound_ctrl:1
	v_fma_mix_f32 v132, v8, v91, v132 op_sel_hi:[0,1,0]
	v_fma_mix_f32 v132, v9, v91, v132 op_sel:[0,1,0] op_sel_hi:[0,1,0]
	v_add_f32_dpp v12, v12, v12 row_ror:2 row_mask:0xf bank_mask:0xf bound_ctrl:1
	v_pk_fma_f32 v[48:49], v[118:119], v[68:69], v[6:7] op_sel:[0,1,0]
	v_pk_fma_f32 v[50:51], v[120:121], v[68:69], v[8:9] op_sel:[0,1,0]
	v_add_f32_dpp v12, v12, v12 row_ror:4 row_mask:0xf bank_mask:0xf bound_ctrl:1
	v_cndmask_b32_e64 v64, v61, v104, s[38:39]
	v_cndmask_b32_e64 v65, v104, v61, s[38:39]
	v_add_f32_dpp v12, v12, v12 row_ror:8 row_mask:0xf bank_mask:0xf bound_ctrl:1
	v_pk_fma_f32 v[6:7], v[114:115], v[12:13], v[48:49] op_sel_hi:[1,0,1] neg_lo:[1,0,0] neg_hi:[1,0,0]
	v_pk_fma_f32 v[8:9], v[116:117], v[12:13], v[50:51] op_sel_hi:[1,0,1] neg_lo:[1,0,0] neg_hi:[1,0,0]
	v_pk_mul_f32 v[6:7], v[6:7], v[106:107]
	v_pk_mul_f32 v[8:9], v[8:9], v[108:109]
	s_waitcnt lgkmcnt(0)
	ds_read_b128 v[88:91], v10 offset:63744
	ds_read_b128 v[96:99], v10 offset:64256
	ds_read_b128 v[92:95], v10 offset:64000
	v_fma_mix_f32 v12, v6, v20, v180 op_sel_hi:[0,1,0]
	v_fma_mix_f32 v12, v7, v20, v12 op_sel:[0,1,0] op_sel_hi:[0,1,0]
	v_fma_mix_f32 v12, v8, v21, v12 op_sel_hi:[0,1,0]
	v_fma_mix_f32 v12, v9, v21, v12 op_sel:[0,1,0] op_sel_hi:[0,1,0]
	v_fma_mix_f32 v133, v6, v112, v180 op_sel_hi:[0,1,0]
	v_fma_mix_f32 v133, v7, v112, v133 op_sel:[0,1,0] op_sel_hi:[0,1,0]
	v_add_f32_dpp v12, v12, v12 row_ror:1 row_mask:0xf bank_mask:0xf bound_ctrl:1
	v_fma_mix_f32 v133, v8, v113, v133 op_sel_hi:[0,1,0]
	v_fma_mix_f32 v133, v9, v113, v133 op_sel:[0,1,0] op_sel_hi:[0,1,0]
	v_add_f32_dpp v12, v12, v12 row_ror:2 row_mask:0xf bank_mask:0xf bound_ctrl:1
	v_pk_fma_f32 v[48:49], v[28:29], v[70:71], v[6:7] op_sel_hi:[1,0,1]
	v_pk_fma_f32 v[50:51], v[30:31], v[70:71], v[8:9] op_sel_hi:[1,0,1]
	v_add_f32_dpp v12, v12, v12 row_ror:4 row_mask:0xf bank_mask:0xf bound_ctrl:1
	v_add_f32_dpp v62, v63, v62 quad_perm:[2,3,0,1] row_mask:0xf bank_mask:0xf bound_ctrl:1
	v_add_f32_dpp v63, v65, v64 quad_perm:[2,3,0,1] row_mask:0xf bank_mask:0xf bound_ctrl:1
	v_add_f32_dpp v12, v12, v12 row_ror:8 row_mask:0xf bank_mask:0xf bound_ctrl:1
	v_pk_fma_f32 v[6:7], v[24:25], v[12:13], v[48:49] op_sel_hi:[1,0,1] neg_lo:[1,0,0] neg_hi:[1,0,0]
	v_pk_fma_f32 v[8:9], v[26:27], v[12:13], v[50:51] op_sel_hi:[1,0,1] neg_lo:[1,0,0] neg_hi:[1,0,0]
	ds_read_b128 v[110:113], v10 offset:64768
	ds_read_b128 v[106:109], v10 offset:64512
	ds_read_b128 v[118:121], v10 offset:65280
	ds_read_b128 v[114:117], v10 offset:65024
	v_fma_mix_f32 v12, v6, v36, v180 op_sel_hi:[0,1,0]
	v_fma_mix_f32 v12, v7, v36, v12 op_sel:[0,1,0] op_sel_hi:[0,1,0]
	v_fma_mix_f32 v12, v8, v37, v12 op_sel_hi:[0,1,0]
	v_fma_mix_f32 v12, v9, v37, v12 op_sel:[0,1,0] op_sel_hi:[0,1,0]
	v_fma_mix_f32 v134, v6, v22, v180 op_sel_hi:[0,1,0]
	v_fma_mix_f32 v134, v7, v22, v134 op_sel:[0,1,0] op_sel_hi:[0,1,0]
	v_add_f32_dpp v12, v12, v12 row_ror:1 row_mask:0xf bank_mask:0xf bound_ctrl:1
	v_fma_mix_f32 v134, v8, v23, v134 op_sel_hi:[0,1,0]
	v_fma_mix_f32 v134, v9, v23, v134 op_sel:[0,1,0] op_sel_hi:[0,1,0]
	v_add_f32_dpp v12, v12, v12 row_ror:2 row_mask:0xf bank_mask:0xf bound_ctrl:1
	v_pk_fma_f32 v[48:49], v[44:45], v[70:71], v[6:7] op_sel:[0,1,0]
	v_pk_fma_f32 v[50:51], v[46:47], v[70:71], v[8:9] op_sel:[0,1,0]
	v_add_f32_dpp v12, v12, v12 row_ror:4 row_mask:0xf bank_mask:0xf bound_ctrl:1
	v_cndmask_b32_e64 v65, v63, v62, s[40:41]
	v_cndmask_b32_e64 v62, v62, v63, s[40:41]
	v_add_f32_dpp v12, v12, v12 row_ror:8 row_mask:0xf bank_mask:0xf bound_ctrl:1
	v_pk_fma_f32 v[6:7], v[40:41], v[12:13], v[48:49] op_sel_hi:[1,0,1] neg_lo:[1,0,0] neg_hi:[1,0,0]
	v_pk_fma_f32 v[8:9], v[42:43], v[12:13], v[50:51] op_sel_hi:[1,0,1] neg_lo:[1,0,0] neg_hi:[1,0,0]
	s_waitcnt lgkmcnt(0)
	v_fma_mix_f32 v12, v6, v88, v180 op_sel_hi:[0,1,0]
	v_fma_mix_f32 v12, v7, v88, v12 op_sel:[0,1,0] op_sel_hi:[0,1,0]
	v_fma_mix_f32 v12, v8, v89, v12 op_sel_hi:[0,1,0]
	v_fma_mix_f32 v12, v9, v89, v12 op_sel:[0,1,0] op_sel_hi:[0,1,0]
	v_fma_mix_f32 v135, v6, v38, v180 op_sel_hi:[0,1,0]
	v_fma_mix_f32 v135, v7, v38, v135 op_sel:[0,1,0] op_sel_hi:[0,1,0]
	v_add_f32_dpp v12, v12, v12 row_ror:1 row_mask:0xf bank_mask:0xf bound_ctrl:1
	v_fma_mix_f32 v135, v8, v39, v135 op_sel_hi:[0,1,0]
	v_fma_mix_f32 v135, v9, v39, v135 op_sel:[0,1,0] op_sel_hi:[0,1,0]
	v_add_f32_dpp v12, v12, v12 row_ror:2 row_mask:0xf bank_mask:0xf bound_ctrl:1
	v_pk_fma_f32 v[48:49], v[96:97], v[72:73], v[6:7] op_sel_hi:[1,0,1]
	v_pk_fma_f32 v[50:51], v[98:99], v[72:73], v[8:9] op_sel_hi:[1,0,1]
	v_add_f32_dpp v12, v12, v12 row_ror:4 row_mask:0xf bank_mask:0xf bound_ctrl:1
	v_add_f32_dpp v62, v62, v65 quad_perm:[1,0,3,2] row_mask:0xf bank_mask:0xf bound_ctrl:1
	v_cvt_pk_bf16_f32 v62, v62, v62
	v_add_f32_dpp v12, v12, v12 row_ror:8 row_mask:0xf bank_mask:0xf bound_ctrl:1
	v_pk_fma_f32 v[6:7], v[92:93], v[12:13], v[48:49] op_sel_hi:[1,0,1] neg_lo:[1,0,0] neg_hi:[1,0,0]
	v_pk_fma_f32 v[8:9], v[94:95], v[12:13], v[50:51] op_sel_hi:[1,0,1] neg_lo:[1,0,0] neg_hi:[1,0,0]
	s_waitcnt lgkmcnt(0)
	s_barrier
	v_xor_b32_e32 v10, 0x10000, v10
	v_xor_b32_e32 v11, 0x1000, v11
	ds_read_b128 v[66:69], v11 offset:0
	ds_read_b128 v[20:23], v10 offset:256
	ds_read_b128 v[28:31], v10 offset:768
	ds_read_b128 v[24:27], v10 offset:512
	ds_read_b128 v[36:39], v10 offset:1280
	ds_read_b128 v[44:47], v10 offset:1792
	ds_read_b128 v[40:43], v10 offset:1536
	v_fma_mix_f32 v12, v6, v110, v180 op_sel_hi:[0,1,0]
	v_fma_mix_f32 v12, v7, v110, v12 op_sel:[0,1,0] op_sel_hi:[0,1,0]
	v_fma_mix_f32 v12, v8, v111, v12 op_sel_hi:[0,1,0]
	v_fma_mix_f32 v12, v9, v111, v12 op_sel:[0,1,0] op_sel_hi:[0,1,0]
	v_fma_mix_f32 v136, v6, v90, v180 op_sel_hi:[0,1,0]
	v_fma_mix_f32 v136, v7, v90, v136 op_sel:[0,1,0] op_sel_hi:[0,1,0]
	v_add_f32_dpp v12, v12, v12 row_ror:1 row_mask:0xf bank_mask:0xf bound_ctrl:1
	v_fma_mix_f32 v136, v8, v91, v136 op_sel_hi:[0,1,0]
	v_fma_mix_f32 v136, v9, v91, v136 op_sel:[0,1,0] op_sel_hi:[0,1,0]
	v_add_f32_dpp v12, v12, v12 row_ror:2 row_mask:0xf bank_mask:0xf bound_ctrl:1
	v_pk_fma_f32 v[48:49], v[118:119], v[72:73], v[6:7] op_sel:[0,1,0]
	v_pk_fma_f32 v[50:51], v[120:121], v[72:73], v[8:9] op_sel:[0,1,0]
	v_add_f32_dpp v12, v12, v12 row_ror:4 row_mask:0xf bank_mask:0xf bound_ctrl:1
	global_store_short v[2:3], v62, off
	v_lshl_add_u64 v[2:3], v[2:3], 0, s[84:85]
	v_add_f32_dpp v12, v12, v12 row_ror:8 row_mask:0xf bank_mask:0xf bound_ctrl:1
	v_pk_fma_f32 v[6:7], v[114:115], v[12:13], v[48:49] op_sel_hi:[1,0,1] neg_lo:[1,0,0] neg_hi:[1,0,0]
	v_pk_fma_f32 v[8:9], v[116:117], v[12:13], v[50:51] op_sel_hi:[1,0,1] neg_lo:[1,0,0] neg_hi:[1,0,0]
	v_pk_mul_f32 v[6:7], v[6:7], v[106:107]
	v_pk_mul_f32 v[8:9], v[8:9], v[108:109]
	v_fma_mix_f32 v137, v6, v112, v180 op_sel_hi:[0,1,0]
	v_fma_mix_f32 v137, v7, v112, v137 op_sel:[0,1,0] op_sel_hi:[0,1,0]
	v_fma_mix_f32 v137, v8, v113, v137 op_sel_hi:[0,1,0]
	v_fma_mix_f32 v137, v9, v113, v137 op_sel:[0,1,0] op_sel_hi:[0,1,0]
	v_add_f32_dpp v130, v130, v130 row_ror:8 row_mask:0xf bank_mask:0xc
	v_add_f32_dpp v130, v122, v122 row_ror:8 row_mask:0xf bank_mask:0x3
	v_add_f32_dpp v131, v131, v131 row_ror:8 row_mask:0xf bank_mask:0xc
	v_add_f32_dpp v131, v123, v123 row_ror:8 row_mask:0xf bank_mask:0x3
	v_add_f32_dpp v132, v132, v132 row_ror:8 row_mask:0xf bank_mask:0xc
	v_add_f32_dpp v132, v124, v124 row_ror:8 row_mask:0xf bank_mask:0x3
	v_add_f32_dpp v133, v133, v133 row_ror:8 row_mask:0xf bank_mask:0xc
	v_add_f32_dpp v133, v125, v125 row_ror:8 row_mask:0xf bank_mask:0x3
	v_add_f32_dpp v134, v134, v134 row_ror:8 row_mask:0xf bank_mask:0xc
	v_add_f32_dpp v134, v126, v126 row_ror:8 row_mask:0xf bank_mask:0x3
	v_add_f32_dpp v135, v135, v135 row_ror:8 row_mask:0xf bank_mask:0xc
	v_add_f32_dpp v135, v127, v127 row_ror:8 row_mask:0xf bank_mask:0x3
	v_add_f32_dpp v136, v136, v136 row_ror:8 row_mask:0xf bank_mask:0xc
	v_add_f32_dpp v136, v128, v128 row_ror:8 row_mask:0xf bank_mask:0x3
	v_add_f32_dpp v137, v137, v137 row_ror:8 row_mask:0xf bank_mask:0xc
	v_add_f32_dpp v137, v129, v129 row_ror:8 row_mask:0xf bank_mask:0x3
	v_add_f32_dpp v134, v134, v134 row_ror:4 row_mask:0xf bank_mask:0xa
	v_add_f32_dpp v134, v130, v130 row_ror:12 row_mask:0xf bank_mask:0x5
	v_add_f32_dpp v135, v135, v135 row_ror:4 row_mask:0xf bank_mask:0xa
	v_add_f32_dpp v135, v131, v131 row_ror:12 row_mask:0xf bank_mask:0x5
	v_add_f32_dpp v136, v136, v136 row_ror:4 row_mask:0xf bank_mask:0xa
	v_add_f32_dpp v136, v132, v132 row_ror:12 row_mask:0xf bank_mask:0x5
	v_add_f32_dpp v137, v137, v137 row_ror:4 row_mask:0xf bank_mask:0xa
	v_add_f32_dpp v137, v133, v133 row_ror:12 row_mask:0xf bank_mask:0x5
	v_cndmask_b32_e64 v62, v136, v134, s[38:39]
	v_cndmask_b32_e64 v63, v134, v136, s[38:39]
	v_cndmask_b32_e64 v64, v137, v135, s[38:39]
	v_cndmask_b32_e64 v65, v135, v137, s[38:39]
	v_add_f32_dpp v62, v63, v62 quad_perm:[2,3,0,1] row_mask:0xf bank_mask:0xf bound_ctrl:1
	s_nop 0
	v_add_f32_dpp v63, v65, v64 quad_perm:[2,3,0,1] row_mask:0xf bank_mask:0xf bound_ctrl:1
	v_cndmask_b32_e64 v65, v63, v62, s[40:41]
	v_cndmask_b32_e64 v62, v62, v63, s[40:41]
	s_nop 1
	v_add_f32_dpp v62, v62, v65 quad_perm:[1,0,3,2] row_mask:0xf bank_mask:0xf bound_ctrl:1
	v_cvt_pk_bf16_f32 v62, v62, v62
	global_store_short v[2:3], v62, off
	s_cmp_lg_u32 s28, 0x800000
	s_cbranch_scc1 .Lscan_cons_chunk
	s_branch .LBB0_53
